# LN row-store write-through with sc1 only (nt hint dropped)
# speedup vs baseline: 1.0020x; 1.0020x over previous
.LBB0_359:
	v_add_f32_e32 v130, v126, v127
	v_add_f32_e32 v131, v128, v129
	v_add_f32_e32 v130, v130, v131
	v_and_b32_e32 v131, 64, v243
	v_add_u32_e32 v131, 64, v131
	v_xor_b32_e32 v132, 1, v243
	v_cmp_lt_i32_e32 vcc, v132, v131
	v_add_f32_e32 v130, v244, v130
	v_lshlrev_b32_e32 v192, 4, v1
	v_cndmask_b32_e32 v132, v243, v132, vcc
	v_lshlrev_b32_e32 v202, 2, v132
	ds_bpermute_b32 v132, v202, v130
	s_and_b32 s2, s69, 0xffff8000
	s_add_i32 s2, s2, 0x8000
	s_waitcnt lgkmcnt(0)
	v_add_f32_e32 v130, v130, v132
	v_xor_b32_e32 v132, 2, v243
	v_cmp_lt_i32_e32 vcc, v132, v131
	s_nop 1
	v_cndmask_b32_e32 v132, v243, v132, vcc
	v_lshlrev_b32_e32 v203, 2, v132
	ds_bpermute_b32 v132, v203, v130
	s_waitcnt lgkmcnt(0)
	v_add_f32_e32 v130, v130, v132
	v_xor_b32_e32 v132, 4, v243
	v_cmp_lt_i32_e32 vcc, v132, v131
	s_nop 1
	v_cndmask_b32_e32 v132, v243, v132, vcc
	v_lshlrev_b32_e32 v204, 2, v132
	ds_bpermute_b32 v132, v204, v130
	s_waitcnt lgkmcnt(0)
	v_add_f32_e32 v130, v130, v132
	v_xor_b32_e32 v132, 8, v243
	v_cmp_lt_i32_e32 vcc, v132, v131
	s_nop 1
	v_cndmask_b32_e32 v132, v243, v132, vcc
	v_lshlrev_b32_e32 v205, 2, v132
	ds_bpermute_b32 v132, v205, v130
	s_waitcnt lgkmcnt(0)
	v_add_f32_e32 v130, v130, v132
	v_xor_b32_e32 v132, 16, v243
	v_cmp_lt_i32_e32 vcc, v132, v131
	s_nop 1
	v_cndmask_b32_e32 v132, v243, v132, vcc
	v_lshlrev_b32_e32 v206, 2, v132
	ds_bpermute_b32 v132, v206, v130
	s_waitcnt lgkmcnt(0)
	v_add_f32_e32 v130, v130, v132
	v_xor_b32_e32 v132, 32, v243
	v_cmp_lt_i32_e32 vcc, v132, v131
	s_nop 1
	v_cndmask_b32_e32 v131, v243, v132, vcc
	v_lshlrev_b32_e32 v207, 2, v131
	ds_bpermute_b32 v131, v207, v130
	s_waitcnt lgkmcnt(0)
	v_add_f32_e32 v144, v130, v131
	v_fmamk_f32 v143, v144, 0xb9800000, v87
	v_fmamk_f32 v142, v144, 0xb9800000, v86
	v_fmamk_f32 v89, v144, 0xb9800000, v89
	v_fmac_f32_e32 v88, 0xb9800000, v144
	v_pk_mul_f32 v[86:87], v[88:89], v[88:89]
	v_pk_mul_f32 v[130:131], v[142:143], v[142:143]
	v_fmamk_f32 v141, v144, 0xb9800000, v79
	v_pk_mov_b32 v[132:133], v[130:131], v[86:87] op_sel:[1,0]
	v_mov_b32_e32 v131, v87
	v_fmamk_f32 v140, v144, 0xb9800000, v78
	v_fmamk_f32 v81, v144, 0xb9800000, v81
	v_fmac_f32_e32 v80, 0xb9800000, v144
	v_fmamk_f32 v138, v144, 0xb9800000, v74
	v_pk_add_f32 v[86:87], v[132:133], v[130:131]
	v_pk_mul_f32 v[78:79], v[80:81], v[80:81]
	v_pk_mul_f32 v[130:131], v[140:141], v[140:141]
	v_fmamk_f32 v139, v144, 0xb9800000, v75
	v_mul_f32_e32 v74, v138, v138
	v_pk_mov_b32 v[132:133], v[130:131], v[78:79] op_sel:[1,0]
	v_mov_b32_e32 v131, v79
	v_fmac_f32_e32 v76, 0xb9800000, v144
	v_pk_fma_f32 v[74:75], v[138:139], v[138:139], v[74:75] op_sel_hi:[1,1,0]
	v_pk_add_f32 v[78:79], v[132:133], v[130:131]
	v_fmamk_f32 v77, v144, 0xb9800000, v77
	v_mul_f32_e32 v74, v76, v76
	v_pk_add_f32 v[86:87], v[86:87], v[86:87] op_sel_hi:[0,1]
	v_pk_add_f32 v[78:79], v[78:79], v[78:79] op_sel_hi:[0,1]
	v_pk_fma_f32 v[130:131], v[76:77], v[76:77], v[74:75] op_sel_hi:[1,1,0]
	v_fmamk_f32 v137, v144, 0xb9800000, v85
	v_fmamk_f32 v136, v144, 0xb9800000, v84
	v_fmamk_f32 v83, v144, 0xb9800000, v83
	v_fmac_f32_e32 v82, 0xb9800000, v144
	v_mul_f32_e32 v74, v82, v82
	v_mul_f32_e32 v130, v83, v83
	v_mul_f32_e32 v86, v136, v136
	v_mul_f32_e32 v78, v137, v137
	v_pk_add_f32 v[74:75], v[74:75], v[130:131]
	v_pk_add_f32 v[78:79], v[86:87], v[78:79]
	v_fmamk_f32 v135, v144, 0xb9800000, v71
	v_fmamk_f32 v134, v144, 0xb9800000, v70
	v_fmamk_f32 v73, v144, 0xb9800000, v73
	v_fmac_f32_e32 v72, 0xb9800000, v144
	v_fmamk_f32 v132, v144, 0xb9800000, v66
	v_pk_add_f32 v[74:75], v[74:75], v[78:79]
	v_pk_mul_f32 v[70:71], v[72:73], v[72:73]
	v_pk_mul_f32 v[78:79], v[134:135], v[134:135]
	v_fmamk_f32 v133, v144, 0xb9800000, v67
	v_mul_f32_e32 v66, v132, v132
	v_pk_mov_b32 v[84:85], v[78:79], v[70:71] op_sel:[1,0]
	v_mov_b32_e32 v79, v71
	v_fmac_f32_e32 v68, 0xb9800000, v144
	v_pk_fma_f32 v[66:67], v[132:133], v[132:133], v[66:67] op_sel_hi:[1,1,0]
	v_pk_add_f32 v[70:71], v[84:85], v[78:79]
	v_fmamk_f32 v69, v144, 0xb9800000, v69
	v_mul_f32_e32 v66, v68, v68
	v_pk_add_f32 v[74:75], v[74:75], v[74:75] op_sel_hi:[0,1]
	v_pk_add_f32 v[70:71], v[70:71], v[70:71] op_sel_hi:[0,1]
	v_pk_fma_f32 v[78:79], v[68:69], v[68:69], v[66:67] op_sel_hi:[1,1,0]
	v_fmamk_f32 v131, v144, 0xb9800000, v93
	v_fmamk_f32 v130, v144, 0xb9800000, v92
	v_fmamk_f32 v91, v144, 0xb9800000, v91
	v_fmac_f32_e32 v90, 0xb9800000, v144
	v_mul_f32_e32 v66, v90, v90
	v_mul_f32_e32 v78, v91, v91
	v_mul_f32_e32 v70, v130, v130
	v_mul_f32_e32 v74, v131, v131
	v_pk_add_f32 v[66:67], v[66:67], v[78:79]
	v_pk_add_f32 v[70:71], v[70:71], v[74:75]
	v_fmamk_f32 v201, v144, 0xb9800000, v95
	v_pk_add_f32 v[66:67], v[66:67], v[70:71]
	v_fmamk_f32 v200, v144, 0xb9800000, v94
	v_fmamk_f32 v97, v144, 0xb9800000, v97
	v_fmac_f32_e32 v96, 0xb9800000, v144
	v_pk_add_f32 v[66:67], v[66:67], v[66:67] op_sel_hi:[0,1]
	v_pk_mul_f32 v[70:71], v[96:97], v[96:97]
	v_pk_mul_f32 v[74:75], v[200:201], v[200:201]
	v_fmamk_f32 v94, v144, 0xb9800000, v98
	v_pk_mov_b32 v[78:79], v[74:75], v[70:71] op_sel:[1,0]
	v_mov_b32_e32 v75, v71
	v_fmamk_f32 v95, v144, 0xb9800000, v99
	v_fmac_f32_e32 v100, 0xb9800000, v144
	v_mul_f32_e32 v66, v94, v94
	v_pk_add_f32 v[70:71], v[78:79], v[74:75]
	v_fmamk_f32 v101, v144, 0xb9800000, v101
	v_pk_fma_f32 v[74:75], v[94:95], v[94:95], v[66:67] op_sel_hi:[1,1,0]
	v_mul_f32_e32 v66, v100, v100
	v_pk_add_f32 v[70:71], v[70:71], v[70:71] op_sel_hi:[0,1]
	v_pk_fma_f32 v[78:79], v[100:101], v[100:101], v[66:67] op_sel_hi:[1,1,0]
	v_fmamk_f32 v93, v144, 0xb9800000, v113
	v_fmamk_f32 v92, v144, 0xb9800000, v112
	v_fmamk_f32 v111, v144, 0xb9800000, v111
	v_fmac_f32_e32 v110, 0xb9800000, v144
	v_mul_f32_e32 v74, v110, v110
	v_mul_f32_e32 v78, v111, v111
	v_mul_f32_e32 v70, v92, v92
	v_mul_f32_e32 v66, v93, v93
	v_pk_add_f32 v[74:75], v[74:75], v[78:79]
	v_pk_add_f32 v[66:67], v[70:71], v[66:67]
	v_fmamk_f32 v87, v144, 0xb9800000, v107
	v_pk_add_f32 v[66:67], v[74:75], v[66:67]
	v_fmamk_f32 v86, v144, 0xb9800000, v106
	v_fmamk_f32 v109, v144, 0xb9800000, v109
	v_fmac_f32_e32 v108, 0xb9800000, v144
	v_pk_add_f32 v[66:67], v[66:67], v[66:67] op_sel_hi:[0,1]
	v_pk_mul_f32 v[70:71], v[108:109], v[108:109]
	v_pk_mul_f32 v[74:75], v[86:87], v[86:87]
	v_fmamk_f32 v84, v144, 0xb9800000, v102
	v_pk_mov_b32 v[78:79], v[74:75], v[70:71] op_sel:[1,0]
	v_mov_b32_e32 v75, v71
	v_fmamk_f32 v85, v144, 0xb9800000, v103
	v_fmac_f32_e32 v104, 0xb9800000, v144
	v_mul_f32_e32 v66, v84, v84
	v_pk_add_f32 v[70:71], v[78:79], v[74:75]
	v_fmamk_f32 v105, v144, 0xb9800000, v105
	v_pk_fma_f32 v[74:75], v[84:85], v[84:85], v[66:67] op_sel_hi:[1,1,0]
	v_mul_f32_e32 v66, v104, v104
	v_pk_add_f32 v[70:71], v[70:71], v[70:71] op_sel_hi:[0,1]
	v_pk_fma_f32 v[98:99], v[104:105], v[104:105], v[66:67] op_sel_hi:[1,1,0]
	v_fmamk_f32 v79, v144, 0xb9800000, v125
	v_fmamk_f32 v78, v144, 0xb9800000, v124
	v_fmamk_f32 v123, v144, 0xb9800000, v123
	v_fmac_f32_e32 v122, 0xb9800000, v144
	v_mul_f32_e32 v74, v122, v122
	v_mul_f32_e32 v98, v123, v123
	v_mul_f32_e32 v70, v78, v78
	v_mul_f32_e32 v66, v79, v79
	v_pk_add_f32 v[74:75], v[74:75], v[98:99]
	v_pk_add_f32 v[66:67], v[70:71], v[66:67]
	v_fmamk_f32 v117, v144, 0xb9800000, v117
	v_pk_add_f32 v[66:67], v[74:75], v[66:67]
	v_fmamk_f32 v75, v144, 0xb9800000, v115
	v_fmamk_f32 v74, v144, 0xb9800000, v114
	v_fmac_f32_e32 v116, 0xb9800000, v144
	v_pk_add_f32 v[98:99], v[66:67], v[66:67] op_sel_hi:[0,1]
	v_pk_mul_f32 v[66:67], v[116:117], v[116:117]
	v_pk_mul_f32 v[70:71], v[74:75], v[74:75]
	v_fmac_f32_e32 v120, 0xb9800000, v144
	v_pk_mov_b32 v[102:103], v[70:71], v[66:67] op_sel:[1,0]
	v_mov_b32_e32 v71, v67
	v_pk_add_f32 v[66:67], v[102:103], v[70:71]
	v_fmamk_f32 v70, v144, 0xb9800000, v118
	v_pk_add_f32 v[102:103], v[66:67], v[66:67] op_sel_hi:[0,1]
	v_fmamk_f32 v71, v144, 0xb9800000, v119
	v_mul_f32_e32 v66, v70, v70
	v_fmamk_f32 v121, v144, 0xb9800000, v121
	v_pk_fma_f32 v[106:107], v[70:71], v[70:71], v[66:67] op_sel_hi:[1,1,0]
	v_mul_f32_e32 v66, v120, v120
	v_pk_fma_f32 v[112:113], v[120:121], v[120:121], v[66:67] op_sel_hi:[1,1,0]
	v_fmamk_f32 v67, v144, 0xb9800000, v129
	v_fmamk_f32 v66, v144, 0xb9800000, v128
	v_fmamk_f32 v127, v144, 0xb9800000, v127
	v_fmac_f32_e32 v126, 0xb9800000, v144
	v_mul_f32_e32 v106, v126, v126
	v_mul_f32_e32 v112, v127, v127
	v_mul_f32_e32 v102, v66, v66
	v_mul_f32_e32 v98, v67, v67
	v_pk_add_f32 v[106:107], v[106:107], v[112:113]
	v_pk_add_f32 v[98:99], v[102:103], v[98:99]
	ds_read_b128 v[112:115], v241
	ds_read_b128 v[144:147], v241 offset:16384
	v_pk_add_f32 v[98:99], v[106:107], v[98:99]
	ds_read_b128 v[148:151], v241 offset:17408
	ds_read_b128 v[208:211], v241 offset:1024
	v_add_f32_e32 v98, v98, v99
	ds_bpermute_b32 v99, v202, v98
	s_waitcnt lgkmcnt(0)
	v_add_f32_e32 v98, v98, v99
	ds_bpermute_b32 v99, v203, v98
	s_waitcnt lgkmcnt(0)
	v_add_f32_e32 v98, v98, v99
	ds_bpermute_b32 v99, v204, v98
	s_waitcnt lgkmcnt(0)
	v_add_f32_e32 v98, v98, v99
	ds_bpermute_b32 v99, v205, v98
	s_waitcnt lgkmcnt(0)
	v_add_f32_e32 v98, v98, v99
	ds_bpermute_b32 v99, v206, v98
	s_waitcnt lgkmcnt(0)
	v_add_f32_e32 v98, v98, v99
	ds_bpermute_b32 v99, v207, v98
	s_waitcnt lgkmcnt(0)
	v_add_f32_e32 v98, v98, v99
	v_fmamk_f32 v98, v98, 0x39800000, v179
	v_mul_f32_e32 v99, 0x4f800000, v98
	v_cmp_gt_f32_e32 vcc, s79, v98
	s_nop 1
	v_cndmask_b32_e32 v98, v98, v99, vcc
	v_sqrt_f32_e32 v99, v98
	s_nop 0
	v_add_u32_e32 v102, -1, v99
	v_fma_f32 v103, -v102, v99, v98
	v_cmp_ge_f32_e64 s[0:1], 0, v103
	v_add_u32_e32 v103, 1, v99
	s_nop 0
	v_cndmask_b32_e64 v102, v99, v102, s[0:1]
	v_fma_f32 v99, -v103, v99, v98
	v_cmp_lt_f32_e64 s[0:1], 0, v99
	s_nop 1
	v_cndmask_b32_e64 v99, v102, v103, s[0:1]
	v_mul_f32_e32 v102, 0x37800000, v99
	v_cndmask_b32_e32 v99, v99, v102, vcc
	v_cmp_class_f32_e32 vcc, v98, v242
	s_nop 1
	v_cndmask_b32_e32 v98, v99, v98, vcc
	v_div_scale_f32 v99, s[0:1], v98, v98, 1.0
	v_rcp_f32_e32 v102, v99
	s_nop 0
	v_fma_f32 v103, -v99, v102, 1.0
	v_fmac_f32_e32 v102, v103, v102
	v_div_scale_f32 v103, vcc, 1.0, v98, 1.0
	v_mul_f32_e32 v106, v103, v102
	v_fma_f32 v107, -v99, v106, v103
	v_fmac_f32_e32 v106, v107, v102
	v_fma_f32 v99, -v99, v106, v103
	v_div_fmas_f32 v99, v99, v102, v106
	v_div_fixup_f32 v102, v99, v98, 1.0
	v_pk_mul_f32 v[88:89], v[88:89], v[102:103] op_sel_hi:[1,0]
	v_pk_mul_f32 v[106:107], v[142:143], v[102:103] op_sel_hi:[1,0]
	v_pk_fma_f32 v[154:155], v[114:115], v[88:89], v[146:147]
	v_pk_fma_f32 v[152:153], v[112:113], v[106:107], v[144:145]
	v_mov_b32_e32 v107, v155
	v_pk_mov_b32 v[88:89], v[152:153], v[154:155] op_sel:[1,0]
	v_mov_b32_e32 v106, v152
	v_pk_add_f32 v[88:89], v[88:89], v[106:107]
	v_pk_mul_f32 v[80:81], v[80:81], v[102:103] op_sel_hi:[1,0]
	v_pk_mul_f32 v[106:107], v[140:141], v[102:103] op_sel_hi:[1,0]
	v_pk_fma_f32 v[150:151], v[210:211], v[80:81], v[150:151]
	v_pk_fma_f32 v[148:149], v[208:209], v[106:107], v[148:149]
	global_store_dwordx4 v192, v[152:155], s[54:55] sc1
	global_store_dwordx4 v192, v[148:151], s[54:55] offset:1024 sc1
	ds_read_b128 v[112:115], v241 offset:18432
	ds_read_b128 v[140:143], v241 offset:2048
	ds_read_b128 v[208:211], v241 offset:19456
	ds_read_b128 v[212:215], v241 offset:3072
	v_pk_mov_b32 v[80:81], v[148:149], v[150:151] op_sel:[1,0]
	v_mov_b32_e32 v106, v148
	v_mov_b32_e32 v107, v151
	v_pk_add_f32 v[80:81], v[80:81], v[106:107]
	v_pk_mul_f32 v[106:107], v[138:139], v[102:103] op_sel_hi:[1,0]
	v_pk_mul_f32 v[76:77], v[76:77], v[102:103] op_sel_hi:[1,0]
	s_waitcnt lgkmcnt(2)
	v_pk_fma_f32 v[144:145], v[140:141], v[106:107], v[112:113]
	v_pk_mul_f32 v[82:83], v[82:83], v[102:103] op_sel_hi:[1,0]
	v_pk_mul_f32 v[112:113], v[136:137], v[102:103] op_sel_hi:[1,0]
	v_add_f32_e32 v88, v88, v89
	v_pk_add_f32 v[80:81], v[80:81], v[80:81] op_sel_hi:[0,1]
	v_pk_fma_f32 v[146:147], v[142:143], v[76:77], v[114:115]
	s_waitcnt lgkmcnt(0)
	v_pk_fma_f32 v[142:143], v[214:215], v[112:113], v[210:211]
	v_pk_fma_f32 v[140:141], v[212:213], v[82:83], v[208:209]
	v_add_f32_e32 v89, 0, v88
	global_store_dwordx4 v192, v[144:147], s[54:55] offset:2048 sc1
	v_add_f32_e32 v77, v144, v145
	v_add_f32_e32 v107, v146, v147
	global_store_dwordx4 v192, v[140:143], s[54:55] offset:3072 sc1
	v_mov_b32_e32 v76, v140
	v_mov_b32_e32 v106, v141
	v_mov_b32_e32 v80, v142
	v_mov_b32_e32 v88, v143
	v_pk_add_f32 v[76:77], v[76:77], v[106:107]
	v_pk_add_f32 v[80:81], v[80:81], v[88:89]
	v_pk_mul_f32 v[88:89], v[134:135], v[102:103] op_sel_hi:[1,0]
	v_pk_add_f32 v[76:77], v[76:77], v[80:81]
	ds_read_b128 v[80:83], v241 offset:4096
	ds_read_b128 v[112:115], v241 offset:20480
	v_pk_mul_f32 v[72:73], v[72:73], v[102:103] op_sel_hi:[1,0]
	ds_read_b128 v[208:211], v241 offset:21504
	ds_read_b128 v[212:215], v241 offset:5120
	v_lshl_add_u64 v[98:99], s[54:55], 0, v[192:193]
	v_pk_mul_f32 v[68:69], v[68:69], v[102:103] op_sel_hi:[1,0]
	s_waitcnt lgkmcnt(2)
	v_pk_fma_f32 v[138:139], v[82:83], v[72:73], v[114:115]
	v_pk_fma_f32 v[136:137], v[80:81], v[88:89], v[112:113]
	v_add_co_u32_e32 v72, vcc, s77, v98
	v_pk_mov_b32 v[80:81], v[136:137], v[138:139] op_sel:[1,0]
	v_mov_b32_e32 v82, v136
	v_mov_b32_e32 v83, v139
	v_addc_co_u32_e32 v73, vcc, 0, v99, vcc
	v_pk_add_f32 v[80:81], v[80:81], v[82:83]
	v_add_co_u32_e32 v118, vcc, s75, v98
	v_pk_add_f32 v[106:107], v[80:81], v[80:81] op_sel_hi:[0,1]
	v_pk_mul_f32 v[80:81], v[132:133], v[102:103] op_sel_hi:[1,0]
	v_addc_co_u32_e32 v119, vcc, 0, v99, vcc
	s_waitcnt lgkmcnt(0)
	v_pk_fma_f32 v[134:135], v[214:215], v[68:69], v[210:211]
	v_pk_fma_f32 v[132:133], v[212:213], v[80:81], v[208:209]
	global_store_dwordx4 v[118:119], v[136:139], off offset:-4096 sc1
	global_store_dwordx4 v[72:73], v[132:135], off offset:1024 sc1
	ds_read_b128 v[80:83], v241 offset:22528
	ds_read_b128 v[112:115], v241 offset:6144
	v_pk_mul_f32 v[128:129], v[90:91], v[102:103] op_sel_hi:[1,0]
	v_pk_mul_f32 v[130:131], v[130:131], v[102:103] op_sel_hi:[1,0]
	ds_read_b128 v[88:91], v241 offset:23552
	ds_read_b128 v[208:211], v241 offset:7168
	v_pk_add_f32 v[76:77], v[76:77], v[76:77] op_sel_hi:[0,1]
	s_waitcnt lgkmcnt(2)
	v_pk_fma_f32 v[130:131], v[114:115], v[130:131], v[82:83]
	v_pk_fma_f32 v[128:129], v[112:113], v[128:129], v[80:81]
	v_add_f32_e32 v69, v132, v133
	v_add_f32_e32 v125, v134, v135
	v_mov_b32_e32 v68, v128
	v_mov_b32_e32 v124, v129
	v_mov_b32_e32 v106, v130
	v_mov_b32_e32 v76, v131
	v_pk_add_f32 v[68:69], v[68:69], v[124:125]
	v_pk_add_f32 v[76:77], v[106:107], v[76:77]
	v_pk_mul_f32 v[80:81], v[96:97], v[102:103] op_sel_hi:[1,0]
	v_pk_add_f32 v[68:69], v[68:69], v[76:77]
	v_pk_mul_f32 v[76:77], v[200:201], v[102:103] op_sel_hi:[1,0]
	s_waitcnt lgkmcnt(0)
	v_pk_fma_f32 v[114:115], v[210:211], v[80:81], v[90:91]
	v_pk_fma_f32 v[112:113], v[208:209], v[76:77], v[88:89]
	global_store_dwordx4 v[72:73], v[128:131], off offset:2048 sc1
	global_store_dwordx4 v[72:73], v[112:115], off offset:3072 sc1
	ds_read_b128 v[80:83], v241 offset:8192
	ds_read_b128 v[88:91], v241 offset:24576
	ds_read_b128 v[208:211], v241 offset:25600
	ds_read_b128 v[212:215], v241 offset:9216
	v_pk_mov_b32 v[72:73], v[112:113], v[114:115] op_sel:[1,0]
	v_mov_b32_e32 v76, v112
	v_mov_b32_e32 v77, v115
	v_pk_add_f32 v[72:73], v[72:73], v[76:77]
	v_pk_mul_f32 v[76:77], v[94:95], v[102:103] op_sel_hi:[1,0]
	v_pk_mul_f32 v[94:95], v[100:101], v[102:103] op_sel_hi:[1,0]
	v_pk_add_f32 v[68:69], v[68:69], v[68:69] op_sel_hi:[0,1]
	s_waitcnt lgkmcnt(2)
	v_pk_fma_f32 v[96:97], v[82:83], v[94:95], v[90:91]
	v_pk_fma_f32 v[94:95], v[80:81], v[76:77], v[88:89]
	v_pk_mul_f32 v[82:83], v[110:111], v[102:103] op_sel_hi:[1,0]
	v_pk_mul_f32 v[88:89], v[92:93], v[102:103] op_sel_hi:[1,0]
	s_waitcnt lgkmcnt(0)
	v_pk_fma_f32 v[90:91], v[212:213], v[82:83], v[208:209]
	v_pk_fma_f32 v[92:93], v[214:215], v[88:89], v[210:211]
	global_store_dwordx4 v[118:119], v[94:97], off sc1
	v_add_f32_e32 v77, v94, v95
	v_add_f32_e32 v81, v96, v97
	global_store_dwordx4 v[118:119], v[90:93], off offset:1024 sc1
	v_mov_b32_e32 v76, v90
	v_mov_b32_e32 v80, v91
	v_pk_add_f32 v[72:73], v[72:73], v[72:73] op_sel_hi:[0,1]
	v_pk_add_f32 v[76:77], v[76:77], v[80:81]
	ds_read_b128 v[80:83], v241 offset:26624
	ds_read_b128 v[208:211], v241 offset:10240
	v_mov_b32_e32 v72, v92
	v_mov_b32_e32 v68, v93
	v_pk_add_f32 v[68:69], v[72:73], v[68:69]
	v_pk_mul_f32 v[72:73], v[86:87], v[102:103] op_sel_hi:[1,0]
	v_pk_add_f32 v[68:69], v[76:77], v[68:69]
	v_pk_mul_f32 v[76:77], v[108:109], v[102:103] op_sel_hi:[1,0]
	ds_read_b128 v[106:109], v241 offset:27648
	ds_read_b128 v[212:215], v241 offset:11264
	s_waitcnt lgkmcnt(2)
	v_pk_fma_f32 v[88:89], v[76:77], v[210:211], v[82:83]
	v_pk_fma_f32 v[86:87], v[72:73], v[208:209], v[80:81]
	v_mov_b32_e32 v77, v89
	v_pk_mov_b32 v[72:73], v[86:87], v[88:89] op_sel:[1,0]
	v_mov_b32_e32 v76, v86
	v_pk_add_f32 v[72:73], v[72:73], v[76:77]
	v_pk_mul_f32 v[76:77], v[84:85], v[102:103] op_sel_hi:[1,0]
	v_pk_mul_f32 v[80:81], v[104:105], v[102:103] op_sel_hi:[1,0]
	s_waitcnt lgkmcnt(0)
	v_pk_fma_f32 v[82:83], v[76:77], v[212:213], v[106:107]
	v_pk_fma_f32 v[84:85], v[80:81], v[214:215], v[108:109]
	global_store_dwordx4 v[118:119], v[86:89], off offset:2048 sc1
	global_store_dwordx4 v[118:119], v[82:85], off offset:3072 sc1
	ds_read_b128 v[104:107], v241 offset:12288
	ds_read_b128 v[108:111], v241 offset:28672
	v_pk_mul_f32 v[118:119], v[122:123], v[102:103] op_sel_hi:[1,0]
	v_pk_mul_f32 v[78:79], v[78:79], v[102:103] op_sel_hi:[1,0]
	v_pk_add_f32 v[68:69], v[68:69], v[68:69] op_sel_hi:[0,1]
	v_pk_add_f32 v[72:73], v[72:73], v[72:73] op_sel_hi:[0,1]
	ds_read_b128 v[122:125], v241 offset:29696
	ds_read_b128 v[208:211], v241 offset:13312
	s_waitcnt lgkmcnt(2)
	v_pk_fma_f32 v[80:81], v[78:79], v[106:107], v[110:111]
	v_pk_fma_f32 v[78:79], v[118:119], v[104:105], v[108:109]
	v_add_f32_e32 v77, v82, v83
	v_add_f32_e32 v101, v84, v85
	v_mov_b32_e32 v76, v78
	v_mov_b32_e32 v100, v79
	v_mov_b32_e32 v72, v80
	v_mov_b32_e32 v68, v81
	v_pk_add_f32 v[76:77], v[76:77], v[100:101]
	v_pk_add_f32 v[68:69], v[72:73], v[68:69]
	v_pk_mul_f32 v[72:73], v[116:117], v[102:103] op_sel_hi:[1,0]
	v_pk_add_f32 v[68:69], v[76:77], v[68:69]
	s_waitcnt lgkmcnt(0)
	v_pk_fma_f32 v[76:77], v[72:73], v[210:211], v[124:125]
	v_pk_add_f32 v[100:101], v[68:69], v[68:69] op_sel:[0,1] op_sel_hi:[1,0]
	v_pk_mul_f32 v[68:69], v[74:75], v[102:103] op_sel_hi:[1,0]
	v_mov_b32_e32 v73, v77
	v_pk_fma_f32 v[74:75], v[68:69], v[208:209], v[122:123]
	ds_read_b128 v[104:107], v241 offset:30720
	ds_read_b128 v[108:111], v241 offset:14336
	v_pk_mov_b32 v[68:69], v[74:75], v[76:77] op_sel:[1,0]
	v_mov_b32_e32 v72, v74
	v_pk_add_f32 v[68:69], v[68:69], v[72:73]
	v_pk_mul_f32 v[66:67], v[66:67], v[102:103] op_sel_hi:[1,0]
	v_pk_add_f32 v[124:125], v[68:69], v[68:69] op_sel:[0,1] op_sel_hi:[1,0]
	v_pk_mul_f32 v[68:69], v[70:71], v[102:103] op_sel_hi:[1,0]
	v_pk_mul_f32 v[70:71], v[120:121], v[102:103] op_sel_hi:[1,0]
	ds_read_b128 v[116:119], v241 offset:31744
	ds_read_b128 v[120:123], v241 offset:15360
	s_waitcnt lgkmcnt(2)
	v_pk_fma_f32 v[72:73], v[70:71], v[110:111], v[106:107]
	v_pk_fma_f32 v[70:71], v[68:69], v[108:109], v[104:105]
	v_pk_mul_f32 v[108:109], v[126:127], v[102:103] op_sel_hi:[1,0]
	v_add_f32_e32 v104, v70, v71
	s_waitcnt lgkmcnt(0)
	v_pk_fma_f32 v[68:69], v[66:67], v[122:123], v[118:119]
	v_pk_fma_f32 v[66:67], v[108:109], v[120:121], v[116:117]
	v_add_f32_e32 v106, v72, v73
	v_mov_b32_e32 v125, v66
	v_mov_b32_e32 v101, v67
	v_mov_b32_e32 v105, v68
	v_mov_b32_e32 v107, v69
	v_pk_add_f32 v[100:101], v[124:125], v[100:101]
	v_pk_add_f32 v[102:103], v[104:105], v[106:107]
	v_add_co_u32_e32 v98, vcc, s78, v98
	v_pk_add_f32 v[100:101], v[100:101], v[102:103]
	s_nop 0
	v_addc_co_u32_e32 v99, vcc, 0, v99, vcc
	v_add_f32_e32 v100, v100, v101
	ds_bpermute_b32 v101, v202, v100
	global_store_dwordx4 v[98:99], v[78:81], off sc1
	global_store_dwordx4 v[98:99], v[74:77], off offset:1024 sc1
	global_store_dwordx4 v[98:99], v[70:73], off offset:2048 sc1
	global_store_dwordx4 v[98:99], v[66:69], off offset:3072 sc1
	s_waitcnt lgkmcnt(0)
	v_add_f32_e32 v100, v100, v101
	ds_bpermute_b32 v101, v203, v100
	s_waitcnt lgkmcnt(0)
	v_add_f32_e32 v100, v100, v101
	ds_bpermute_b32 v101, v204, v100
	s_waitcnt lgkmcnt(0)
	v_add_f32_e32 v100, v100, v101
	ds_bpermute_b32 v101, v205, v100
	s_waitcnt lgkmcnt(0)
	v_add_f32_e32 v100, v100, v101
	ds_bpermute_b32 v101, v206, v100
	s_waitcnt lgkmcnt(0)
	v_add_f32_e32 v100, v100, v101
	ds_bpermute_b32 v101, v207, v100
	s_waitcnt lgkmcnt(0)
	v_add_f32_e32 v106, v100, v101
	v_fmamk_f32 v153, v106, 0xb9800000, v153
	v_fmac_f32_e32 v152, 0xb9800000, v106
	v_fmamk_f32 v155, v106, 0xb9800000, v155
	v_fmac_f32_e32 v154, 0xb9800000, v106
	v_pk_mul_f32 v[98:99], v[154:155], v[154:155]
	v_pk_mul_f32 v[100:101], v[152:153], v[152:153]
	v_fmamk_f32 v149, v106, 0xb9800000, v149
	v_pk_mov_b32 v[102:103], v[100:101], v[98:99] op_sel:[1,0]
	v_mov_b32_e32 v101, v99
	v_pk_add_f32 v[98:99], v[102:103], v[100:101]
	v_fmac_f32_e32 v148, 0xb9800000, v106
	v_fmamk_f32 v151, v106, 0xb9800000, v151
	v_fmac_f32_e32 v150, 0xb9800000, v106
	v_pk_add_f32 v[98:99], v[98:99], v[98:99] op_sel_hi:[0,1]
	v_pk_mul_f32 v[100:101], v[150:151], v[150:151]
	v_pk_mul_f32 v[102:103], v[148:149], v[148:149]
	v_fmac_f32_e32 v144, 0xb9800000, v106
	v_pk_mov_b32 v[104:105], v[102:103], v[100:101] op_sel:[1,0]
	v_mov_b32_e32 v103, v101
	v_fmamk_f32 v145, v106, 0xb9800000, v145
	v_fmac_f32_e32 v146, 0xb9800000, v106
	v_mul_f32_e32 v98, v144, v144
	v_pk_add_f32 v[100:101], v[104:105], v[102:103]
	v_fmamk_f32 v147, v106, 0xb9800000, v147
	v_pk_fma_f32 v[102:103], v[144:145], v[144:145], v[98:99] op_sel_hi:[1,1,0]
	v_mul_f32_e32 v98, v146, v146
	v_pk_add_f32 v[100:101], v[100:101], v[100:101] op_sel_hi:[0,1]
	v_pk_fma_f32 v[104:105], v[146:147], v[146:147], v[98:99] op_sel_hi:[1,1,0]
	v_fmamk_f32 v143, v106, 0xb9800000, v143
	v_fmac_f32_e32 v142, 0xb9800000, v106
	v_fmamk_f32 v141, v106, 0xb9800000, v141
	v_fmac_f32_e32 v140, 0xb9800000, v106
	v_mul_f32_e32 v102, v140, v140
	v_mul_f32_e32 v104, v141, v141
	v_mul_f32_e32 v98, v142, v142
	v_mul_f32_e32 v100, v143, v143
	v_pk_add_f32 v[102:103], v[102:103], v[104:105]
	v_pk_add_f32 v[98:99], v[98:99], v[100:101]
	v_fmamk_f32 v137, v106, 0xb9800000, v137
	v_pk_add_f32 v[98:99], v[102:103], v[98:99]
	v_fmac_f32_e32 v136, 0xb9800000, v106
	v_fmamk_f32 v139, v106, 0xb9800000, v139
	v_fmac_f32_e32 v138, 0xb9800000, v106
	v_pk_add_f32 v[98:99], v[98:99], v[98:99] op_sel_hi:[0,1]
	v_pk_mul_f32 v[100:101], v[138:139], v[138:139]
	v_pk_mul_f32 v[102:103], v[136:137], v[136:137]
	v_fmac_f32_e32 v132, 0xb9800000, v106
	v_pk_mov_b32 v[104:105], v[102:103], v[100:101] op_sel:[1,0]
	v_mov_b32_e32 v103, v101
	v_fmamk_f32 v133, v106, 0xb9800000, v133
	v_fmac_f32_e32 v134, 0xb9800000, v106
	v_mul_f32_e32 v98, v132, v132
	v_pk_add_f32 v[100:101], v[104:105], v[102:103]
	v_fmamk_f32 v135, v106, 0xb9800000, v135
	v_pk_fma_f32 v[102:103], v[132:133], v[132:133], v[98:99] op_sel_hi:[1,1,0]
	v_mul_f32_e32 v98, v134, v134
	v_pk_add_f32 v[100:101], v[100:101], v[100:101] op_sel_hi:[0,1]
	v_pk_fma_f32 v[104:105], v[134:135], v[134:135], v[98:99] op_sel_hi:[1,1,0]
	v_fmamk_f32 v131, v106, 0xb9800000, v131
	v_fmac_f32_e32 v130, 0xb9800000, v106
	v_fmamk_f32 v129, v106, 0xb9800000, v129
	v_fmac_f32_e32 v128, 0xb9800000, v106
	v_mul_f32_e32 v102, v128, v128
	v_mul_f32_e32 v104, v129, v129
	v_mul_f32_e32 v100, v130, v130
	v_mul_f32_e32 v98, v131, v131
	v_pk_add_f32 v[102:103], v[102:103], v[104:105]
	v_pk_add_f32 v[98:99], v[100:101], v[98:99]
	v_fmamk_f32 v113, v106, 0xb9800000, v113
	v_pk_add_f32 v[98:99], v[102:103], v[98:99]
	v_fmac_f32_e32 v112, 0xb9800000, v106
	v_fmamk_f32 v115, v106, 0xb9800000, v115
	v_fmac_f32_e32 v114, 0xb9800000, v106
	v_pk_add_f32 v[98:99], v[98:99], v[98:99] op_sel_hi:[0,1]
	v_pk_mul_f32 v[100:101], v[114:115], v[114:115]
	v_pk_mul_f32 v[102:103], v[112:113], v[112:113]
	v_fmac_f32_e32 v94, 0xb9800000, v106
	v_pk_mov_b32 v[104:105], v[102:103], v[100:101] op_sel:[1,0]
	v_mov_b32_e32 v103, v101
	v_fmamk_f32 v95, v106, 0xb9800000, v95
	v_fmac_f32_e32 v96, 0xb9800000, v106
	v_mul_f32_e32 v98, v94, v94
	v_pk_add_f32 v[100:101], v[104:105], v[102:103]
	v_fmamk_f32 v97, v106, 0xb9800000, v97
	v_pk_fma_f32 v[102:103], v[94:95], v[94:95], v[98:99] op_sel_hi:[1,1,0]
	v_mul_f32_e32 v98, v96, v96
	v_pk_add_f32 v[100:101], v[100:101], v[100:101] op_sel_hi:[0,1]
	v_pk_fma_f32 v[104:105], v[96:97], v[96:97], v[98:99] op_sel_hi:[1,1,0]
	v_fmamk_f32 v93, v106, 0xb9800000, v93
	v_fmac_f32_e32 v92, 0xb9800000, v106
	v_fmamk_f32 v91, v106, 0xb9800000, v91
	v_fmac_f32_e32 v90, 0xb9800000, v106
	v_mul_f32_e32 v102, v90, v90
	v_mul_f32_e32 v104, v91, v91
	v_mul_f32_e32 v100, v92, v92
	v_mul_f32_e32 v98, v93, v93
	v_pk_add_f32 v[102:103], v[102:103], v[104:105]
	v_pk_add_f32 v[98:99], v[100:101], v[98:99]
	v_fmamk_f32 v87, v106, 0xb9800000, v87
	v_pk_add_f32 v[98:99], v[102:103], v[98:99]
	v_fmac_f32_e32 v86, 0xb9800000, v106
	v_fmamk_f32 v89, v106, 0xb9800000, v89
	v_fmac_f32_e32 v88, 0xb9800000, v106
	v_pk_add_f32 v[98:99], v[98:99], v[98:99] op_sel_hi:[0,1]
	v_pk_mul_f32 v[100:101], v[88:89], v[88:89]
	v_pk_mul_f32 v[102:103], v[86:87], v[86:87]
	v_fmac_f32_e32 v82, 0xb9800000, v106
	v_pk_mov_b32 v[104:105], v[102:103], v[100:101] op_sel:[1,0]
	v_mov_b32_e32 v103, v101
	v_fmamk_f32 v83, v106, 0xb9800000, v83
	v_fmac_f32_e32 v84, 0xb9800000, v106
	v_mul_f32_e32 v98, v82, v82
	v_pk_add_f32 v[100:101], v[104:105], v[102:103]
	v_fmamk_f32 v85, v106, 0xb9800000, v85
	v_pk_fma_f32 v[102:103], v[82:83], v[82:83], v[98:99] op_sel_hi:[1,1,0]
	v_mul_f32_e32 v98, v84, v84
	v_pk_add_f32 v[100:101], v[100:101], v[100:101] op_sel_hi:[0,1]
	v_pk_fma_f32 v[104:105], v[84:85], v[84:85], v[98:99] op_sel_hi:[1,1,0]
	v_fmamk_f32 v81, v106, 0xb9800000, v81
	v_fmac_f32_e32 v80, 0xb9800000, v106
	v_fmamk_f32 v79, v106, 0xb9800000, v79
	v_fmac_f32_e32 v78, 0xb9800000, v106
	v_mul_f32_e32 v102, v78, v78
	v_mul_f32_e32 v104, v79, v79
	v_mul_f32_e32 v100, v80, v80
	v_mul_f32_e32 v98, v81, v81
	v_pk_add_f32 v[102:103], v[102:103], v[104:105]
	v_pk_add_f32 v[98:99], v[100:101], v[98:99]
	v_fmamk_f32 v75, v106, 0xb9800000, v75
	v_pk_add_f32 v[98:99], v[102:103], v[98:99]
	v_fmac_f32_e32 v74, 0xb9800000, v106
	v_fmamk_f32 v77, v106, 0xb9800000, v77
	v_fmac_f32_e32 v76, 0xb9800000, v106
	v_pk_add_f32 v[98:99], v[98:99], v[98:99] op_sel_hi:[0,1]
	v_pk_mul_f32 v[100:101], v[76:77], v[76:77]
	v_pk_mul_f32 v[102:103], v[74:75], v[74:75]
	v_fmac_f32_e32 v70, 0xb9800000, v106
	v_pk_mov_b32 v[104:105], v[102:103], v[100:101] op_sel:[1,0]
	v_mov_b32_e32 v103, v101
	v_fmamk_f32 v71, v106, 0xb9800000, v71
	v_fmac_f32_e32 v72, 0xb9800000, v106
	v_mul_f32_e32 v98, v70, v70
	v_pk_add_f32 v[100:101], v[104:105], v[102:103]
	v_fmamk_f32 v73, v106, 0xb9800000, v73
	v_pk_fma_f32 v[102:103], v[70:71], v[70:71], v[98:99] op_sel_hi:[1,1,0]
	v_mul_f32_e32 v98, v72, v72
	v_pk_add_f32 v[100:101], v[100:101], v[100:101] op_sel_hi:[0,1]
	v_pk_fma_f32 v[104:105], v[72:73], v[72:73], v[98:99] op_sel_hi:[1,1,0]
	v_fmamk_f32 v69, v106, 0xb9800000, v69
	v_fmac_f32_e32 v68, 0xb9800000, v106
	v_fmamk_f32 v67, v106, 0xb9800000, v67
	v_fmac_f32_e32 v66, 0xb9800000, v106
	v_mul_f32_e32 v102, v66, v66
	v_mul_f32_e32 v104, v67, v67
	v_mul_f32_e32 v100, v68, v68
	v_mul_f32_e32 v98, v69, v69
	v_pk_add_f32 v[102:103], v[102:103], v[104:105]
	v_pk_add_f32 v[98:99], v[100:101], v[98:99]
	s_nop 0
	v_pk_add_f32 v[98:99], v[102:103], v[98:99]
	s_nop 0
	v_add_f32_e32 v98, v98, v99
	ds_bpermute_b32 v99, v202, v98
	s_waitcnt lgkmcnt(0)
	v_add_f32_e32 v98, v98, v99
	ds_bpermute_b32 v99, v203, v98
	s_waitcnt lgkmcnt(0)
	v_add_f32_e32 v98, v98, v99
	ds_bpermute_b32 v99, v204, v98
	s_waitcnt lgkmcnt(0)
	v_add_f32_e32 v98, v98, v99
	ds_bpermute_b32 v99, v205, v98
	s_waitcnt lgkmcnt(0)
	v_add_f32_e32 v98, v98, v99
	ds_bpermute_b32 v99, v206, v98
	s_waitcnt lgkmcnt(0)
	v_add_f32_e32 v98, v98, v99
	ds_bpermute_b32 v99, v207, v98
	s_waitcnt lgkmcnt(0)
	v_add_f32_e32 v98, v98, v99
	v_fmamk_f32 v98, v98, 0x39800000, v179
	v_mul_f32_e32 v99, 0x4f800000, v98
	v_cmp_gt_f32_e32 vcc, s79, v98
	s_nop 1
	v_cndmask_b32_e32 v98, v98, v99, vcc
	v_sqrt_f32_e32 v99, v98
	s_nop 0
	v_add_u32_e32 v100, -1, v99
	v_fma_f32 v101, -v100, v99, v98
	v_cmp_ge_f32_e64 s[0:1], 0, v101
	v_add_u32_e32 v101, 1, v99
	s_nop 0
	v_cndmask_b32_e64 v100, v99, v100, s[0:1]
	v_fma_f32 v99, -v101, v99, v98
	v_cmp_lt_f32_e64 s[0:1], 0, v99
	s_nop 1
	v_cndmask_b32_e64 v99, v100, v101, s[0:1]
	v_mul_f32_e32 v100, 0x37800000, v99
	v_cndmask_b32_e32 v99, v99, v100, vcc
	v_cmp_class_f32_e32 vcc, v98, v242
	s_nop 1
	v_cndmask_b32_e32 v98, v99, v98, vcc
	v_div_scale_f32 v99, s[0:1], v98, v98, 1.0
	v_rcp_f32_e32 v100, v99
	s_lshl_b64 s[0:1], s[46:47], 12
	s_and_b64 s[8:9], s[48:49], exec
	s_cselect_b32 s2, 0, s2
	v_fma_f32 v101, -v99, v100, 1.0
	v_fmac_f32_e32 v100, v101, v100
	v_div_scale_f32 v101, vcc, 1.0, v98, 1.0
	v_mul_f32_e32 v102, v101, v100
	v_fma_f32 v103, -v99, v102, v101
	v_fmac_f32_e32 v102, v103, v100
	v_fma_f32 v99, -v99, v102, v101
	v_div_fmas_f32 v104, v99, v100, v102
	v_add_u32_e32 v99, s2, v241
	ds_read_b128 v[100:103], v99 offset:49152
	ds_read_b128 v[108:111], v99 offset:50176
	v_div_fixup_f32 v98, v104, v98, 1.0
	ds_read_b128 v[104:107], v99 offset:32768
	ds_read_b128 v[116:119], v99 offset:33792
	v_pk_mul_f32 v[120:121], v[152:153], v[98:99] op_sel_hi:[1,0]
	s_waitcnt lgkmcnt(3)
	v_pk_add_f32 v[100:101], v[100:101], 1.0 op_sel_hi:[1,0]
	v_pk_add_f32 v[102:103], v[102:103], 1.0 op_sel_hi:[1,0]
	s_waitcnt lgkmcnt(1)
	v_pk_fma_f32 v[104:105], v[100:101], v[120:121], v[104:105]
	v_mov_b32_e32 v120, v193
	v_cvt_pk_fp8_f32 v120, v104, v105
	v_pk_mul_f32 v[100:101], v[154:155], v[98:99] op_sel_hi:[1,0]
	v_pk_add_f32 v[108:109], v[108:109], 1.0 op_sel_hi:[1,0]
	v_pk_fma_f32 v[106:107], v[102:103], v[100:101], v[106:107]
	v_lshl_add_u64 v[100:101], v[198:199], 0, s[0:1]
	v_cvt_pk_fp8_f32 v120, v106, v107 op_sel:[0,0,1]
	v_pk_add_f32 v[110:111], v[110:111], 1.0 op_sel_hi:[1,0]
	s_lshl_b64 s[0:1], s[46:47], 13
	v_lshl_add_u64 v[102:103], v[194:195], 0, s[0:1]
	global_store_dword v[100:101], v120, off
	v_bfe_u32 v120, v104, 16, 1
	v_add3_u32 v104, v104, v120, s80
	v_bfe_u32 v120, v105, 16, 1
	v_add3_u32 v105, v105, v120, s80
	v_pk_mul_f32 v[120:121], v[148:149], v[98:99] op_sel_hi:[1,0]
	v_lshrrev_b32_e32 v104, 16, v104
	s_waitcnt lgkmcnt(0)
	v_pk_fma_f32 v[108:109], v[108:109], v[120:121], v[116:117]
	v_mov_b32_e32 v120, v193
	v_cvt_pk_fp8_f32 v120, v108, v109
	v_pk_mul_f32 v[116:117], v[150:151], v[98:99] op_sel_hi:[1,0]
	v_and_or_b32 v104, v105, s76, v104
	v_bfe_u32 v105, v106, 16, 1
	v_pk_fma_f32 v[124:125], v[110:111], v[116:117], v[118:119]
	v_add3_u32 v105, v106, v105, s80
	v_bfe_u32 v106, v107, 16, 1
	v_cvt_pk_fp8_f32 v120, v124, v125 op_sel:[0,0,1]
	v_lshrrev_b32_e32 v105, 16, v105
	v_add3_u32 v106, v107, v106, s80
	v_and_or_b32 v105, v106, s76, v105
	global_store_dwordx2 v[102:103], v[104:105], off
	global_store_dword v[100:101], v120, off offset:256
	v_bfe_u32 v104, v108, 16, 1
	v_add3_u32 v104, v108, v104, s80
	v_bfe_u32 v105, v109, 16, 1
	v_lshrrev_b32_e32 v104, 16, v104
	v_add3_u32 v105, v109, v105, s80
	v_and_or_b32 v126, v105, s76, v104
	v_bfe_u32 v104, v124, 16, 1
	v_add3_u32 v104, v124, v104, s80
	v_lshrrev_b32_e32 v124, 16, v104
	ds_read_b128 v[104:107], v99 offset:51200
	ds_read_b128 v[116:119], v99 offset:52224
	ds_read_b128 v[108:111], v99 offset:34816
	ds_read_b128 v[120:123], v99 offset:35840
	v_pk_mul_f32 v[144:145], v[144:145], v[98:99] op_sel_hi:[1,0]
	s_waitcnt lgkmcnt(3)
	v_pk_add_f32 v[104:105], v[104:105], 1.0 op_sel_hi:[1,0]
	v_bfe_u32 v127, v125, 16, 1
	s_waitcnt lgkmcnt(1)
	v_pk_fma_f32 v[104:105], v[104:105], v[144:145], v[108:109]
	v_pk_mul_f32 v[108:109], v[146:147], v[98:99] op_sel_hi:[1,0]
	v_pk_add_f32 v[106:107], v[106:107], 1.0 op_sel_hi:[1,0]
	v_mov_b32_e32 v144, v193
	v_pk_fma_f32 v[106:107], v[106:107], v[108:109], v[110:111]
	v_add3_u32 v108, v125, v127, s80
	v_and_or_b32 v127, v108, s76, v124
	v_bfe_u32 v108, v104, 16, 1
	v_cvt_pk_fp8_f32 v144, v104, v105
	v_add3_u32 v104, v104, v108, s80
	v_bfe_u32 v108, v105, 16, 1
	v_add3_u32 v105, v105, v108, s80
	v_pk_mul_f32 v[108:109], v[140:141], v[98:99] op_sel_hi:[1,0]
	v_pk_add_f32 v[110:111], v[116:117], 1.0 op_sel_hi:[1,0]
	v_lshrrev_b32_e32 v104, 16, v104
	s_waitcnt lgkmcnt(0)
	v_pk_fma_f32 v[108:109], v[110:111], v[108:109], v[120:121]
	v_mov_b32_e32 v120, v193
	v_cvt_pk_fp8_f32 v120, v108, v109
	v_pk_mul_f32 v[110:111], v[142:143], v[98:99] op_sel_hi:[1,0]
	v_pk_add_f32 v[116:117], v[118:119], 1.0 op_sel_hi:[1,0]
	v_and_or_b32 v104, v105, s76, v104
	v_bfe_u32 v105, v106, 16, 1
	v_pk_fma_f32 v[110:111], v[116:117], v[110:111], v[122:123]
	v_cvt_pk_fp8_f32 v144, v106, v107 op_sel:[0,0,1]
	v_add3_u32 v105, v106, v105, s80
	v_bfe_u32 v106, v107, 16, 1
	v_cvt_pk_fp8_f32 v120, v110, v111 op_sel:[0,0,1]
	v_lshrrev_b32_e32 v105, 16, v105
	v_add3_u32 v106, v107, v106, s80
	v_and_or_b32 v105, v106, s76, v105
	global_store_dwordx2 v[102:103], v[126:127], off offset:512
	global_store_dword v[100:101], v144, off offset:512
	global_store_dwordx2 v[102:103], v[104:105], off offset:1024
	global_store_dword v[100:101], v120, off offset:768
	v_bfe_u32 v104, v108, 16, 1
	v_add3_u32 v104, v108, v104, s80
	v_bfe_u32 v105, v109, 16, 1
	v_lshrrev_b32_e32 v104, 16, v104
	v_add3_u32 v105, v109, v105, s80
	v_and_or_b32 v104, v105, s76, v104
	v_bfe_u32 v105, v110, 16, 1
	v_add3_u32 v105, v110, v105, s80
	v_bfe_u32 v106, v111, 16, 1
	v_lshrrev_b32_e32 v105, 16, v105
	v_add3_u32 v106, v111, v106, s80
	v_and_or_b32 v105, v106, s76, v105
	global_store_dwordx2 v[102:103], v[104:105], off offset:1536
	ds_read_b128 v[104:107], v99 offset:53248
	ds_read_b128 v[108:111], v99 offset:36864
	v_pk_mul_f32 v[124:125], v[136:137], v[98:99] op_sel_hi:[1,0]
	ds_read_b128 v[116:119], v99 offset:54272
	ds_read_b128 v[120:123], v99 offset:37888
	s_waitcnt lgkmcnt(3)
	v_pk_add_f32 v[104:105], v[104:105], 1.0 op_sel_hi:[1,0]
	v_pk_add_f32 v[106:107], v[106:107], 1.0 op_sel_hi:[1,0]
	s_waitcnt lgkmcnt(2)
	v_pk_fma_f32 v[104:105], v[104:105], v[124:125], v[108:109]
	v_mov_b32_e32 v124, v193
	v_cvt_pk_fp8_f32 v124, v104, v105
	v_pk_mul_f32 v[108:109], v[138:139], v[98:99] op_sel_hi:[1,0]
	v_pk_mul_f32 v[128:129], v[128:129], v[98:99] op_sel_hi:[1,0]
	v_pk_fma_f32 v[106:107], v[106:107], v[108:109], v[110:111]
	v_bfe_u32 v108, v104, 16, 1
	v_add3_u32 v104, v104, v108, s80
	v_bfe_u32 v108, v105, 16, 1
	v_add3_u32 v105, v105, v108, s80
	v_pk_mul_f32 v[108:109], v[132:133], v[98:99] op_sel_hi:[1,0]
	s_waitcnt lgkmcnt(1)
	v_pk_add_f32 v[110:111], v[116:117], 1.0 op_sel_hi:[1,0]
	v_cvt_pk_fp8_f32 v124, v106, v107 op_sel:[0,0,1]
	s_waitcnt lgkmcnt(0)
	v_pk_fma_f32 v[108:109], v[108:109], v[110:111], v[120:121]
	v_mov_b32_e32 v120, v193
	v_cvt_pk_fp8_f32 v120, v108, v109
	v_lshrrev_b32_e32 v104, 16, v104
	v_pk_mul_f32 v[110:111], v[134:135], v[98:99] op_sel_hi:[1,0]
	v_pk_add_f32 v[116:117], v[118:119], 1.0 op_sel_hi:[1,0]
	global_store_dword v[100:101], v124, off offset:1024
	v_and_or_b32 v104, v105, s76, v104
	v_bfe_u32 v105, v106, 16, 1
	v_pk_fma_f32 v[124:125], v[110:111], v[116:117], v[122:123]
	v_add3_u32 v105, v106, v105, s80
	v_bfe_u32 v106, v107, 16, 1
	v_cvt_pk_fp8_f32 v120, v124, v125 op_sel:[0,0,1]
	v_lshrrev_b32_e32 v105, 16, v105
	v_add3_u32 v106, v107, v106, s80
	v_and_or_b32 v105, v106, s76, v105
	global_store_dwordx2 v[102:103], v[104:105], off offset:2048
	global_store_dword v[100:101], v120, off offset:1280
	v_bfe_u32 v104, v108, 16, 1
	v_add3_u32 v104, v108, v104, s80
	v_bfe_u32 v105, v109, 16, 1
	v_lshrrev_b32_e32 v104, 16, v104
	v_add3_u32 v105, v109, v105, s80
	v_and_or_b32 v126, v105, s76, v104
	v_bfe_u32 v104, v124, 16, 1
	v_add3_u32 v104, v124, v104, s80
	v_lshrrev_b32_e32 v124, 16, v104
	ds_read_b128 v[104:107], v99 offset:55296
	ds_read_b128 v[116:119], v99 offset:56320
	ds_read_b128 v[108:111], v99 offset:38912
	ds_read_b128 v[120:123], v99 offset:39936
	v_bfe_u32 v127, v125, 16, 1
	s_waitcnt lgkmcnt(3)
	v_pk_add_f32 v[104:105], v[104:105], 1.0 op_sel_hi:[1,0]
	v_pk_add_f32 v[106:107], v[106:107], 1.0 op_sel_hi:[1,0]
	s_waitcnt lgkmcnt(1)
	v_pk_fma_f32 v[104:105], v[128:129], v[104:105], v[108:109]
	v_pk_mul_f32 v[108:109], v[130:131], v[98:99] op_sel_hi:[1,0]
	v_mov_b32_e32 v128, v193
	v_pk_fma_f32 v[106:107], v[108:109], v[106:107], v[110:111]
	v_add3_u32 v108, v125, v127, s80
	v_and_or_b32 v127, v108, s76, v124
	v_bfe_u32 v108, v104, 16, 1
	v_cvt_pk_fp8_f32 v128, v104, v105
	v_add3_u32 v104, v104, v108, s80
	v_bfe_u32 v108, v105, 16, 1
	v_add3_u32 v105, v105, v108, s80
	v_pk_mul_f32 v[108:109], v[112:113], v[98:99] op_sel_hi:[1,0]
	v_pk_add_f32 v[110:111], v[116:117], 1.0 op_sel_hi:[1,0]
	v_mov_b32_e32 v116, v193
	s_waitcnt lgkmcnt(0)
	v_pk_fma_f32 v[108:109], v[108:109], v[110:111], v[120:121]
	v_lshrrev_b32_e32 v104, 16, v104
	v_cvt_pk_fp8_f32 v116, v108, v109
	v_pk_mul_f32 v[110:111], v[114:115], v[98:99] op_sel_hi:[1,0]
	v_pk_add_f32 v[112:113], v[118:119], 1.0 op_sel_hi:[1,0]
	v_and_or_b32 v104, v105, s76, v104
	v_bfe_u32 v105, v106, 16, 1
	v_pk_fma_f32 v[110:111], v[110:111], v[112:113], v[122:123]
	v_cvt_pk_fp8_f32 v128, v106, v107 op_sel:[0,0,1]
	v_add3_u32 v105, v106, v105, s80
	v_bfe_u32 v106, v107, 16, 1
	v_cvt_pk_fp8_f32 v116, v110, v111 op_sel:[0,0,1]
	v_lshrrev_b32_e32 v105, 16, v105
	v_add3_u32 v106, v107, v106, s80
	v_and_or_b32 v105, v106, s76, v105
	global_store_dwordx2 v[102:103], v[126:127], off offset:2560
	global_store_dword v[100:101], v128, off offset:1536
	global_store_dwordx2 v[102:103], v[104:105], off offset:3072
	global_store_dword v[100:101], v116, off offset:1792
	v_bfe_u32 v104, v108, 16, 1
	v_add3_u32 v104, v108, v104, s80
	v_bfe_u32 v105, v109, 16, 1
	v_lshrrev_b32_e32 v104, 16, v104
	v_add3_u32 v105, v109, v105, s80
	v_and_or_b32 v104, v105, s76, v104
	v_bfe_u32 v105, v110, 16, 1
	v_add3_u32 v105, v110, v105, s80
	v_bfe_u32 v106, v111, 16, 1
	v_lshrrev_b32_e32 v105, 16, v105
	v_add3_u32 v106, v111, v106, s80
	v_and_or_b32 v105, v106, s76, v105
	global_store_dwordx2 v[102:103], v[104:105], off offset:3584
	ds_read_b128 v[104:107], v99 offset:57344
	ds_read_b128 v[108:111], v99 offset:40960
	v_pk_mul_f32 v[94:95], v[94:95], v[98:99] op_sel_hi:[1,0]
	v_pk_mul_f32 v[96:97], v[96:97], v[98:99] op_sel_hi:[1,0]
	ds_read_b128 v[112:115], v99 offset:58368
	ds_read_b128 v[116:119], v99 offset:41984
	s_waitcnt lgkmcnt(3)
	v_pk_add_f32 v[104:105], v[104:105], 1.0 op_sel_hi:[1,0]
	v_pk_mul_f32 v[90:91], v[90:91], v[98:99] op_sel_hi:[1,0]
	s_waitcnt lgkmcnt(2)
	v_pk_fma_f32 v[94:95], v[94:95], v[104:105], v[108:109]
	v_mov_b32_e32 v108, v193
	v_pk_add_f32 v[104:105], v[106:107], 1.0 op_sel_hi:[1,0]
	v_cvt_pk_fp8_f32 v108, v94, v95
	v_pk_fma_f32 v[96:97], v[96:97], v[104:105], v[110:111]
	v_bfe_u32 v104, v94, 16, 1
	v_add3_u32 v94, v94, v104, s80
	v_bfe_u32 v104, v95, 16, 1
	v_lshrrev_b32_e32 v94, 16, v94
	v_add3_u32 v95, v95, v104, s80
	v_and_or_b32 v94, v95, s76, v94
	v_bfe_u32 v95, v96, 16, 1
	v_cvt_pk_fp8_f32 v108, v96, v97 op_sel:[0,0,1]
	v_add3_u32 v95, v96, v95, s80
	v_bfe_u32 v96, v97, 16, 1
	v_lshrrev_b32_e32 v95, 16, v95
	v_add3_u32 v96, v97, v96, s80
	v_and_or_b32 v95, v96, s76, v95
	s_waitcnt lgkmcnt(1)
	v_pk_add_f32 v[96:97], v[112:113], 1.0 op_sel_hi:[1,0]
	v_mov_b32_e32 v104, v193
	s_waitcnt lgkmcnt(0)
	v_pk_fma_f32 v[96:97], v[90:91], v[96:97], v[116:117]
	v_pk_mul_f32 v[90:91], v[92:93], v[98:99] op_sel_hi:[1,0]
	v_cvt_pk_fp8_f32 v104, v96, v97
	v_pk_add_f32 v[92:93], v[114:115], 1.0 op_sel_hi:[1,0]
	global_store_dword v[100:101], v108, off offset:2048
	v_pk_fma_f32 v[114:115], v[90:91], v[92:93], v[118:119]
	v_bfe_u32 v92, v96, 16, 1
	v_cvt_pk_fp8_f32 v104, v114, v115 op_sel:[0,0,1]
	v_add3_u32 v92, v96, v92, s80
	v_bfe_u32 v93, v97, 16, 1
	v_add_co_u32_e32 v90, vcc, s77, v102
	v_lshrrev_b32_e32 v92, 16, v92
	v_add3_u32 v93, v97, v93, s80
	v_addc_co_u32_e32 v91, vcc, 0, v103, vcc
	v_and_or_b32 v96, v93, s76, v92
	v_bfe_u32 v92, v114, 16, 1
	global_store_dwordx2 v[90:91], v[94:95], off
	global_store_dword v[100:101], v104, off offset:2304
	v_add3_u32 v92, v114, v92, s80
	v_lshrrev_b32_e32 v97, 16, v92
	ds_read_b128 v[92:95], v99 offset:59392
	ds_read_b128 v[106:109], v99 offset:60416
	ds_read_b128 v[102:105], v99 offset:43008
	ds_read_b128 v[110:113], v99 offset:44032
	v_pk_mul_f32 v[86:87], v[86:87], v[98:99] op_sel_hi:[1,0]
	s_waitcnt lgkmcnt(3)
	v_pk_add_f32 v[92:93], v[92:93], 1.0 op_sel_hi:[1,0]
	v_bfe_u32 v114, v115, 16, 1
	s_waitcnt lgkmcnt(1)
	v_pk_fma_f32 v[86:87], v[86:87], v[92:93], v[102:103]
	v_pk_mul_f32 v[88:89], v[88:89], v[98:99] op_sel_hi:[1,0]
	v_pk_add_f32 v[92:93], v[94:95], 1.0 op_sel_hi:[1,0]
	v_mov_b32_e32 v102, v193
	v_pk_fma_f32 v[88:89], v[88:89], v[92:93], v[104:105]
	v_add3_u32 v92, v115, v114, s80
	v_and_or_b32 v97, v92, s76, v97
	v_bfe_u32 v92, v86, 16, 1
	v_cvt_pk_fp8_f32 v102, v86, v87
	v_add3_u32 v86, v86, v92, s80
	v_bfe_u32 v92, v87, 16, 1
	v_add3_u32 v87, v87, v92, s80
	v_pk_mul_f32 v[82:83], v[82:83], v[98:99] op_sel_hi:[1,0]
	v_pk_add_f32 v[92:93], v[106:107], 1.0 op_sel_hi:[1,0]
	v_mov_b32_e32 v94, v193
	s_waitcnt lgkmcnt(0)
	v_pk_fma_f32 v[82:83], v[82:83], v[92:93], v[110:111]
	v_lshrrev_b32_e32 v86, 16, v86
	v_cvt_pk_fp8_f32 v94, v82, v83
	v_pk_mul_f32 v[84:85], v[84:85], v[98:99] op_sel_hi:[1,0]
	v_pk_add_f32 v[92:93], v[108:109], 1.0 op_sel_hi:[1,0]
	v_and_or_b32 v86, v87, s76, v86
	v_bfe_u32 v87, v88, 16, 1
	v_pk_fma_f32 v[84:85], v[84:85], v[92:93], v[112:113]
	v_cvt_pk_fp8_f32 v102, v88, v89 op_sel:[0,0,1]
	v_add3_u32 v87, v88, v87, s80
	v_bfe_u32 v88, v89, 16, 1
	v_cvt_pk_fp8_f32 v94, v84, v85 op_sel:[0,0,1]
	v_lshrrev_b32_e32 v87, 16, v87
	v_add3_u32 v88, v89, v88, s80
	v_and_or_b32 v87, v88, s76, v87
	global_store_dwordx2 v[90:91], v[96:97], off offset:512
	global_store_dword v[100:101], v102, off offset:2560
	global_store_dwordx2 v[90:91], v[86:87], off offset:1024
	global_store_dword v[100:101], v94, off offset:2816
	v_bfe_u32 v86, v82, 16, 1
	v_add3_u32 v82, v82, v86, s80
	v_bfe_u32 v86, v83, 16, 1
	v_lshrrev_b32_e32 v82, 16, v82
	v_add3_u32 v83, v83, v86, s80
	v_and_or_b32 v82, v83, s76, v82
	v_bfe_u32 v83, v84, 16, 1
	v_add3_u32 v83, v84, v83, s80
	v_bfe_u32 v84, v85, 16, 1
	v_lshrrev_b32_e32 v83, 16, v83
	v_add3_u32 v84, v85, v84, s80
	v_and_or_b32 v83, v84, s76, v83
	global_store_dwordx2 v[90:91], v[82:83], off offset:1536
	ds_read_b128 v[82:85], v99 offset:61440
	ds_read_b128 v[86:89], v99 offset:45056
	ds_read_b128 v[92:95], v99 offset:62464
	ds_read_b128 v[102:105], v99 offset:46080
	v_pk_mul_f32 v[78:79], v[78:79], v[98:99] op_sel_hi:[1,0]
	s_waitcnt lgkmcnt(3)
	v_pk_add_f32 v[82:83], v[82:83], 1.0 op_sel_hi:[1,0]
	v_pk_mul_f32 v[80:81], v[80:81], v[98:99] op_sel_hi:[1,0]
	s_waitcnt lgkmcnt(2)
	v_pk_fma_f32 v[78:79], v[78:79], v[82:83], v[86:87]
	v_pk_add_f32 v[82:83], v[84:85], 1.0 op_sel_hi:[1,0]
	v_mov_b32_e32 v86, v193
	v_pk_fma_f32 v[80:81], v[80:81], v[82:83], v[88:89]
	v_bfe_u32 v82, v78, 16, 1
	v_cvt_pk_fp8_f32 v86, v78, v79
	v_add3_u32 v78, v78, v82, s80
	v_bfe_u32 v82, v79, 16, 1
	v_add3_u32 v79, v79, v82, s80
	v_pk_mul_f32 v[74:75], v[74:75], v[98:99] op_sel_hi:[1,0]
	s_waitcnt lgkmcnt(1)
	v_pk_add_f32 v[82:83], v[92:93], 1.0 op_sel_hi:[1,0]
	v_lshrrev_b32_e32 v78, 16, v78
	s_waitcnt lgkmcnt(0)
	v_pk_fma_f32 v[74:75], v[74:75], v[82:83], v[102:103]
	v_mov_b32_e32 v84, v193
	v_and_or_b32 v78, v79, s76, v78
	v_bfe_u32 v79, v80, 16, 1
	v_cvt_pk_fp8_f32 v84, v74, v75
	v_cvt_pk_fp8_f32 v86, v80, v81 op_sel:[0,0,1]
	v_add3_u32 v79, v80, v79, s80
	v_bfe_u32 v80, v81, 16, 1
	v_pk_mul_f32 v[76:77], v[76:77], v[98:99] op_sel_hi:[1,0]
	v_pk_add_f32 v[82:83], v[94:95], 1.0 op_sel_hi:[1,0]
	v_lshrrev_b32_e32 v79, 16, v79
	v_pk_fma_f32 v[92:93], v[76:77], v[82:83], v[104:105]
	v_add3_u32 v76, v81, v80, s80
	v_and_or_b32 v79, v76, s76, v79
	v_bfe_u32 v76, v74, 16, 1
	v_cvt_pk_fp8_f32 v84, v92, v93 op_sel:[0,0,1]
	v_add3_u32 v74, v74, v76, s80
	v_bfe_u32 v76, v75, 16, 1
	v_lshrrev_b32_e32 v74, 16, v74
	v_add3_u32 v75, v75, v76, s80
	v_and_or_b32 v94, v75, s76, v74
	v_bfe_u32 v74, v92, 16, 1
	global_store_dword v[100:101], v86, off offset:3072
	global_store_dwordx2 v[90:91], v[78:79], off offset:2048
	global_store_dword v[100:101], v84, off offset:3328
	v_add3_u32 v74, v92, v74, s80
	v_lshrrev_b32_e32 v92, 16, v74
	ds_read_b128 v[74:77], v99 offset:63488
	ds_read_b128 v[82:85], v99 offset:64512
	ds_read_b128 v[78:81], v99 offset:47104
	ds_read_b128 v[86:89], v99 offset:48128
	v_pk_mul_f32 v[70:71], v[70:71], v[98:99] op_sel_hi:[1,0]
	s_waitcnt lgkmcnt(3)
	v_pk_add_f32 v[74:75], v[74:75], 1.0 op_sel_hi:[1,0]
	v_bfe_u32 v95, v93, 16, 1
	s_waitcnt lgkmcnt(1)
	v_pk_fma_f32 v[70:71], v[70:71], v[74:75], v[78:79]
	v_pk_mul_f32 v[72:73], v[72:73], v[98:99] op_sel_hi:[1,0]
	v_pk_add_f32 v[74:75], v[76:77], 1.0 op_sel_hi:[1,0]
	v_mov_b32_e32 v78, v193
	v_pk_fma_f32 v[72:73], v[72:73], v[74:75], v[80:81]
	v_add3_u32 v74, v93, v95, s80
	v_and_or_b32 v95, v74, s76, v92
	v_bfe_u32 v74, v70, 16, 1
	v_cvt_pk_fp8_f32 v78, v70, v71
	v_add3_u32 v70, v70, v74, s80
	v_bfe_u32 v74, v71, 16, 1
	v_add3_u32 v71, v71, v74, s80
	v_pk_mul_f32 v[66:67], v[66:67], v[98:99] op_sel_hi:[1,0]
	v_pk_add_f32 v[74:75], v[82:83], 1.0 op_sel_hi:[1,0]
	v_mov_b32_e32 v76, v193
	s_waitcnt lgkmcnt(0)
	v_pk_fma_f32 v[66:67], v[66:67], v[74:75], v[86:87]
	v_lshrrev_b32_e32 v70, 16, v70
	v_cvt_pk_fp8_f32 v76, v66, v67
	v_pk_mul_f32 v[68:69], v[68:69], v[98:99] op_sel_hi:[1,0]
	v_pk_add_f32 v[74:75], v[84:85], 1.0 op_sel_hi:[1,0]
	v_and_or_b32 v70, v71, s76, v70
	v_bfe_u32 v71, v72, 16, 1
	v_pk_fma_f32 v[68:69], v[68:69], v[74:75], v[88:89]
	v_cvt_pk_fp8_f32 v78, v72, v73 op_sel:[0,0,1]
	v_add3_u32 v71, v72, v71, s80
	v_bfe_u32 v72, v73, 16, 1
	v_cvt_pk_fp8_f32 v76, v68, v69 op_sel:[0,0,1]
	v_lshrrev_b32_e32 v71, 16, v71
	v_add3_u32 v72, v73, v72, s80
	v_and_or_b32 v71, v72, s76, v71
	global_store_dwordx2 v[90:91], v[94:95], off offset:2560
	global_store_dword v[100:101], v78, off offset:3584
	global_store_dwordx2 v[90:91], v[70:71], off offset:3072
	global_store_dword v[100:101], v76, off offset:3840
	v_bfe_u32 v70, v66, 16, 1
	v_add3_u32 v66, v66, v70, s80
	v_bfe_u32 v70, v67, 16, 1
	v_lshrrev_b32_e32 v66, 16, v66
	v_add3_u32 v67, v67, v70, s80
	v_and_or_b32 v66, v67, s76, v66
	v_bfe_u32 v67, v68, 16, 1
	v_add3_u32 v67, v68, v67, s80
	v_bfe_u32 v68, v69, 16, 1
	v_lshrrev_b32_e32 v67, 16, v67
	v_add3_u32 v68, v69, v68, s80
	v_and_or_b32 v67, v68, s76, v67
	global_store_dwordx2 v[90:91], v[66:67], off offset:3584
	s_add_u32 s26, s26, s34
	s_addc_u32 s27, s27, s35
	s_add_u32 s4, s4, s6
	s_addc_u32 s5, s5, s7
	s_add_i32 s69, s69, s74
	s_andn2_b64 vcc, exec, s[52:53]
	s_mov_b32 s46, s50
	s_cbranch_vccz .LBB0_374

.LBB0_868:
	v_add_f32_e32 v130, v126, v127
	v_add_f32_e32 v131, v128, v129
	v_add_f32_e32 v130, v130, v131
	v_and_b32_e32 v131, 64, v241
	v_add_u32_e32 v131, 64, v131
	v_xor_b32_e32 v132, 1, v241
	v_cmp_lt_i32_e32 vcc, v132, v131
	v_add_f32_e32 v130, v242, v130
	s_and_b32 s2, s19, 0xffff8000
	v_cndmask_b32_e32 v132, v241, v132, vcc
	v_lshlrev_b32_e32 v185, 2, v132
	ds_bpermute_b32 v132, v185, v130
	s_add_i32 s2, s2, 0x8000
	s_waitcnt lgkmcnt(0)
	v_add_f32_e32 v130, v130, v132
	v_xor_b32_e32 v132, 2, v241
	v_cmp_lt_i32_e32 vcc, v132, v131
	s_nop 1
	v_cndmask_b32_e32 v132, v241, v132, vcc
	v_lshlrev_b32_e32 v190, 2, v132
	ds_bpermute_b32 v132, v190, v130
	s_waitcnt lgkmcnt(0)
	v_add_f32_e32 v130, v130, v132
	v_xor_b32_e32 v132, 4, v241
	v_cmp_lt_i32_e32 vcc, v132, v131
	s_nop 1
	v_cndmask_b32_e32 v132, v241, v132, vcc
	v_lshlrev_b32_e32 v191, 2, v132
	ds_bpermute_b32 v132, v191, v130
	s_waitcnt lgkmcnt(0)
	v_add_f32_e32 v130, v130, v132
	v_xor_b32_e32 v132, 8, v241
	v_cmp_lt_i32_e32 vcc, v132, v131
	s_nop 1
	v_cndmask_b32_e32 v132, v241, v132, vcc
	v_lshlrev_b32_e32 v192, 2, v132
	ds_bpermute_b32 v132, v192, v130
	s_waitcnt lgkmcnt(0)
	v_add_f32_e32 v130, v130, v132
	v_xor_b32_e32 v132, 16, v241
	v_cmp_lt_i32_e32 vcc, v132, v131
	s_nop 1
	v_cndmask_b32_e32 v132, v241, v132, vcc
	v_lshlrev_b32_e32 v193, 2, v132
	ds_bpermute_b32 v132, v193, v130
	s_waitcnt lgkmcnt(0)
	v_add_f32_e32 v130, v130, v132
	v_xor_b32_e32 v132, 32, v241
	v_cmp_lt_i32_e32 vcc, v132, v131
	s_nop 1
	v_cndmask_b32_e32 v131, v241, v132, vcc
	v_lshlrev_b32_e32 v194, 2, v131
	ds_bpermute_b32 v131, v194, v130
	s_waitcnt lgkmcnt(0)
	v_add_f32_e32 v182, v130, v131
	v_fmamk_f32 v87, v182, 0xb9800000, v87
	v_fmamk_f32 v86, v182, 0xb9800000, v86
	v_fmamk_f32 v89, v182, 0xb9800000, v89
	v_fmac_f32_e32 v88, 0xb9800000, v182
	v_pk_mul_f32 v[130:131], v[88:89], v[88:89]
	v_pk_mul_f32 v[132:133], v[86:87], v[86:87]
	v_fmamk_f32 v189, v182, 0xb9800000, v79
	v_pk_mov_b32 v[134:135], v[132:133], v[130:131] op_sel:[1,0]
	v_mov_b32_e32 v133, v131
	v_fmamk_f32 v188, v182, 0xb9800000, v78
	v_fmamk_f32 v81, v182, 0xb9800000, v81
	v_fmac_f32_e32 v80, 0xb9800000, v182
	v_pk_add_f32 v[130:131], v[134:135], v[132:133]
	v_pk_mul_f32 v[78:79], v[80:81], v[80:81]
	v_pk_mul_f32 v[132:133], v[188:189], v[188:189]
	v_fmac_f32_e32 v76, 0xb9800000, v182
	v_pk_mov_b32 v[134:135], v[132:133], v[78:79] op_sel:[1,0]
	v_mov_b32_e32 v133, v79
	v_pk_add_f32 v[78:79], v[134:135], v[132:133]
	v_fmamk_f32 v77, v182, 0xb9800000, v77
	v_pk_add_f32 v[132:133], v[78:79], v[78:79] op_sel_hi:[0,1]
	v_fmamk_f32 v78, v182, 0xb9800000, v74
	v_fmamk_f32 v79, v182, 0xb9800000, v75
	v_mul_f32_e32 v74, v78, v78
	v_pk_fma_f32 v[134:135], v[78:79], v[78:79], v[74:75] op_sel_hi:[1,1,0]
	v_mul_f32_e32 v74, v76, v76
	v_pk_add_f32 v[130:131], v[130:131], v[130:131] op_sel_hi:[0,1]
	v_pk_fma_f32 v[136:137], v[76:77], v[76:77], v[74:75] op_sel_hi:[1,1,0]
	v_fmamk_f32 v75, v182, 0xb9800000, v85
	v_fmamk_f32 v74, v182, 0xb9800000, v84
	v_fmamk_f32 v83, v182, 0xb9800000, v83
	v_fmac_f32_e32 v82, 0xb9800000, v182
	v_mul_f32_e32 v134, v82, v82
	v_mul_f32_e32 v136, v83, v83
	v_mul_f32_e32 v130, v74, v74
	v_mul_f32_e32 v132, v75, v75
	v_pk_add_f32 v[84:85], v[134:135], v[136:137]
	v_pk_add_f32 v[130:131], v[130:131], v[132:133]
	v_fmamk_f32 v71, v182, 0xb9800000, v71
	v_fmamk_f32 v70, v182, 0xb9800000, v70
	v_fmamk_f32 v73, v182, 0xb9800000, v73
	v_fmac_f32_e32 v72, 0xb9800000, v182
	v_fmamk_f32 v186, v182, 0xb9800000, v66
	v_pk_add_f32 v[84:85], v[84:85], v[130:131]
	v_pk_mul_f32 v[130:131], v[72:73], v[72:73]
	v_pk_mul_f32 v[132:133], v[70:71], v[70:71]
	v_fmamk_f32 v187, v182, 0xb9800000, v67
	v_mul_f32_e32 v66, v186, v186
	v_pk_mov_b32 v[134:135], v[132:133], v[130:131] op_sel:[1,0]
	v_mov_b32_e32 v133, v131
	v_fmac_f32_e32 v68, 0xb9800000, v182
	v_pk_fma_f32 v[66:67], v[186:187], v[186:187], v[66:67] op_sel_hi:[1,1,0]
	v_pk_add_f32 v[130:131], v[134:135], v[132:133]
	v_fmamk_f32 v69, v182, 0xb9800000, v69
	v_mul_f32_e32 v66, v68, v68
	v_pk_add_f32 v[84:85], v[84:85], v[84:85] op_sel_hi:[0,1]
	v_pk_add_f32 v[130:131], v[130:131], v[130:131] op_sel_hi:[0,1]
	v_pk_fma_f32 v[132:133], v[68:69], v[68:69], v[66:67] op_sel_hi:[1,1,0]
	v_fmamk_f32 v139, v182, 0xb9800000, v93
	v_fmamk_f32 v138, v182, 0xb9800000, v92
	v_fmamk_f32 v91, v182, 0xb9800000, v91
	v_fmac_f32_e32 v90, 0xb9800000, v182
	v_mul_f32_e32 v66, v90, v90
	v_mul_f32_e32 v132, v91, v91
	v_mul_f32_e32 v130, v138, v138
	v_mul_f32_e32 v84, v139, v139
	v_pk_add_f32 v[66:67], v[66:67], v[132:133]
	v_pk_add_f32 v[84:85], v[130:131], v[84:85]
	v_fmamk_f32 v135, v182, 0xb9800000, v95
	v_pk_add_f32 v[66:67], v[66:67], v[84:85]
	v_fmamk_f32 v134, v182, 0xb9800000, v94
	v_fmamk_f32 v97, v182, 0xb9800000, v97
	v_fmac_f32_e32 v96, 0xb9800000, v182
	v_pk_add_f32 v[84:85], v[66:67], v[66:67] op_sel_hi:[0,1]
	v_pk_mul_f32 v[66:67], v[96:97], v[96:97]
	v_pk_mul_f32 v[92:93], v[134:135], v[134:135]
	v_fmac_f32_e32 v100, 0xb9800000, v182
	v_pk_mov_b32 v[94:95], v[92:93], v[66:67] op_sel:[1,0]
	v_mov_b32_e32 v93, v67
	v_pk_add_f32 v[66:67], v[94:95], v[92:93]
	v_fmamk_f32 v101, v182, 0xb9800000, v101
	v_pk_add_f32 v[92:93], v[66:67], v[66:67] op_sel_hi:[0,1]
	v_fmamk_f32 v66, v182, 0xb9800000, v98
	v_fmamk_f32 v67, v182, 0xb9800000, v99
	v_mul_f32_e32 v84, v66, v66
	v_pk_fma_f32 v[94:95], v[66:67], v[66:67], v[84:85] op_sel_hi:[1,1,0]
	v_mul_f32_e32 v84, v100, v100
	v_pk_fma_f32 v[98:99], v[100:101], v[100:101], v[84:85] op_sel_hi:[1,1,0]
	v_fmamk_f32 v131, v182, 0xb9800000, v113
	v_fmamk_f32 v130, v182, 0xb9800000, v112
	v_fmamk_f32 v111, v182, 0xb9800000, v111
	v_fmac_f32_e32 v110, 0xb9800000, v182
	v_mul_f32_e32 v94, v110, v110
	v_mul_f32_e32 v98, v111, v111
	v_mul_f32_e32 v92, v130, v130
	v_mul_f32_e32 v84, v131, v131
	v_pk_add_f32 v[94:95], v[94:95], v[98:99]
	v_pk_add_f32 v[84:85], v[92:93], v[84:85]
	v_fmamk_f32 v107, v182, 0xb9800000, v107
	v_pk_add_f32 v[84:85], v[94:95], v[84:85]
	v_fmamk_f32 v106, v182, 0xb9800000, v106
	v_fmamk_f32 v109, v182, 0xb9800000, v109
	v_fmac_f32_e32 v108, 0xb9800000, v182
	v_pk_add_f32 v[84:85], v[84:85], v[84:85] op_sel_hi:[0,1]
	v_pk_mul_f32 v[92:93], v[108:109], v[108:109]
	v_pk_mul_f32 v[94:95], v[106:107], v[106:107]
	v_fmamk_f32 v102, v182, 0xb9800000, v102
	v_pk_mov_b32 v[98:99], v[94:95], v[92:93] op_sel:[1,0]
	v_mov_b32_e32 v95, v93
	v_fmamk_f32 v103, v182, 0xb9800000, v103
	v_fmac_f32_e32 v104, 0xb9800000, v182
	v_mul_f32_e32 v84, v102, v102
	v_pk_add_f32 v[92:93], v[98:99], v[94:95]
	v_fmamk_f32 v105, v182, 0xb9800000, v105
	v_pk_fma_f32 v[94:95], v[102:103], v[102:103], v[84:85] op_sel_hi:[1,1,0]
	v_mul_f32_e32 v84, v104, v104
	v_pk_add_f32 v[92:93], v[92:93], v[92:93] op_sel_hi:[0,1]
	v_pk_fma_f32 v[98:99], v[104:105], v[104:105], v[84:85] op_sel_hi:[1,1,0]
	v_fmamk_f32 v133, v182, 0xb9800000, v125
	v_fmamk_f32 v132, v182, 0xb9800000, v124
	v_fmamk_f32 v123, v182, 0xb9800000, v123
	v_fmac_f32_e32 v122, 0xb9800000, v182
	v_mul_f32_e32 v94, v122, v122
	v_mul_f32_e32 v98, v123, v123
	v_mul_f32_e32 v92, v132, v132
	v_mul_f32_e32 v84, v133, v133
	v_pk_add_f32 v[94:95], v[94:95], v[98:99]
	v_pk_add_f32 v[84:85], v[92:93], v[84:85]
	v_fmamk_f32 v137, v182, 0xb9800000, v115
	v_pk_add_f32 v[84:85], v[94:95], v[84:85]
	v_fmamk_f32 v136, v182, 0xb9800000, v114
	v_fmamk_f32 v117, v182, 0xb9800000, v117
	v_fmac_f32_e32 v116, 0xb9800000, v182
	v_pk_add_f32 v[84:85], v[84:85], v[84:85] op_sel_hi:[0,1]
	v_pk_mul_f32 v[92:93], v[116:117], v[116:117]
	v_pk_mul_f32 v[94:95], v[136:137], v[136:137]
	v_fmamk_f32 v124, v182, 0xb9800000, v118
	v_pk_mov_b32 v[98:99], v[94:95], v[92:93] op_sel:[1,0]
	v_mov_b32_e32 v95, v93
	v_fmamk_f32 v125, v182, 0xb9800000, v119
	v_fmac_f32_e32 v120, 0xb9800000, v182
	v_mul_f32_e32 v84, v124, v124
	v_pk_add_f32 v[92:93], v[98:99], v[94:95]
	v_fmamk_f32 v121, v182, 0xb9800000, v121
	v_pk_fma_f32 v[94:95], v[124:125], v[124:125], v[84:85] op_sel_hi:[1,1,0]
	v_mul_f32_e32 v84, v120, v120
	v_pk_add_f32 v[92:93], v[92:93], v[92:93] op_sel_hi:[0,1]
	v_pk_fma_f32 v[98:99], v[120:121], v[120:121], v[84:85] op_sel_hi:[1,1,0]
	v_fmamk_f32 v119, v182, 0xb9800000, v129
	v_fmamk_f32 v118, v182, 0xb9800000, v128
	v_fmamk_f32 v127, v182, 0xb9800000, v127
	v_fmac_f32_e32 v126, 0xb9800000, v182
	v_mul_f32_e32 v94, v126, v126
	v_mul_f32_e32 v98, v127, v127
	v_mul_f32_e32 v92, v118, v118
	v_mul_f32_e32 v84, v119, v119
	v_pk_add_f32 v[94:95], v[94:95], v[98:99]
	v_pk_add_f32 v[84:85], v[92:93], v[84:85]
	v_lshl_add_u64 v[182:183], s[40:41], 0, v[180:181]
	v_pk_add_f32 v[84:85], v[94:95], v[84:85]
	s_nop 0
	v_add_f32_e32 v84, v84, v85
	ds_bpermute_b32 v85, v185, v84
	s_waitcnt lgkmcnt(0)
	v_add_f32_e32 v84, v84, v85
	ds_bpermute_b32 v85, v190, v84
	s_waitcnt lgkmcnt(0)
	v_add_f32_e32 v84, v84, v85
	ds_bpermute_b32 v85, v191, v84
	s_waitcnt lgkmcnt(0)
	v_add_f32_e32 v84, v84, v85
	ds_bpermute_b32 v85, v192, v84
	s_waitcnt lgkmcnt(0)
	v_add_f32_e32 v84, v84, v85
	ds_bpermute_b32 v85, v193, v84
	s_waitcnt lgkmcnt(0)
	v_add_f32_e32 v84, v84, v85
	ds_bpermute_b32 v85, v194, v84
	s_waitcnt lgkmcnt(0)
	v_add_f32_e32 v84, v84, v85
	v_fmamk_f32 v84, v84, 0x39800000, v179
	v_mul_f32_e32 v85, 0x4f800000, v84
	v_cmp_gt_f32_e32 vcc, s48, v84
	s_nop 1
	v_cndmask_b32_e32 v84, v84, v85, vcc
	v_sqrt_f32_e32 v85, v84
	s_nop 0
	v_add_u32_e32 v92, -1, v85
	v_fma_f32 v93, -v92, v85, v84
	v_cmp_ge_f32_e64 s[0:1], 0, v93
	v_add_u32_e32 v93, 1, v85
	s_nop 0
	v_cndmask_b32_e64 v92, v85, v92, s[0:1]
	v_fma_f32 v85, -v93, v85, v84
	v_cmp_lt_f32_e64 s[0:1], 0, v85
	s_nop 1
	v_cndmask_b32_e64 v85, v92, v93, s[0:1]
	v_mul_f32_e32 v92, 0x37800000, v85
	v_cndmask_b32_e32 v85, v85, v92, vcc
	v_cmp_class_f32_e32 vcc, v84, v237
	s_nop 1
	v_cndmask_b32_e32 v84, v85, v84, vcc
	v_div_scale_f32 v85, s[0:1], v84, v84, 1.0
	v_rcp_f32_e32 v92, v85
	s_nop 0
	v_fma_f32 v93, -v85, v92, 1.0
	v_fmac_f32_e32 v92, v93, v92
	v_div_scale_f32 v93, vcc, 1.0, v84, 1.0
	v_mul_f32_e32 v94, v93, v92
	v_fma_f32 v95, -v85, v94, v93
	v_fmac_f32_e32 v94, v95, v92
	v_fma_f32 v85, -v85, v94, v93
	v_div_fmas_f32 v85, v85, v92, v94
	ds_read_b128 v[92:95], v236
	ds_read_b128 v[112:115], v236 offset:16384
	v_div_fixup_f32 v184, v85, v84, 1.0
	ds_read_b128 v[196:199], v236 offset:17408
	ds_read_b128 v[200:203], v236 offset:1024
	v_pk_mul_f32 v[88:89], v[88:89], v[184:185] op_sel_hi:[1,0]
	v_pk_mul_f32 v[84:85], v[86:87], v[184:185] op_sel_hi:[1,0]
	s_waitcnt lgkmcnt(2)
	v_pk_fma_f32 v[86:87], v[94:95], v[88:89], v[114:115]
	v_pk_fma_f32 v[84:85], v[92:93], v[84:85], v[112:113]
	v_mov_b32_e32 v93, v87
	v_pk_mov_b32 v[88:89], v[84:85], v[86:87] op_sel:[1,0]
	v_mov_b32_e32 v92, v84
	v_pk_add_f32 v[88:89], v[88:89], v[92:93]
	v_pk_mul_f32 v[80:81], v[80:81], v[184:185] op_sel_hi:[1,0]
	v_pk_mul_f32 v[92:93], v[188:189], v[184:185] op_sel_hi:[1,0]
	s_waitcnt lgkmcnt(0)
	v_pk_fma_f32 v[94:95], v[202:203], v[80:81], v[198:199]
	v_pk_fma_f32 v[92:93], v[200:201], v[92:93], v[196:197]
	global_store_dwordx4 v180, v[84:87], s[40:41] sc1
	global_store_dwordx4 v180, v[92:95], s[40:41] offset:1024 sc1
	ds_read_b128 v[112:115], v236 offset:18432
	ds_read_b128 v[196:199], v236 offset:2048
	ds_read_b128 v[200:203], v236 offset:19456
	ds_read_b128 v[204:207], v236 offset:3072
	v_pk_mov_b32 v[80:81], v[92:93], v[94:95] op_sel:[1,0]
	v_mov_b32_e32 v98, v92
	v_mov_b32_e32 v99, v95
	v_pk_add_f32 v[80:81], v[80:81], v[98:99]
	v_pk_mul_f32 v[76:77], v[76:77], v[184:185] op_sel_hi:[1,0]
	v_pk_mul_f32 v[78:79], v[78:79], v[184:185] op_sel_hi:[1,0]
	v_pk_mul_f32 v[82:83], v[82:83], v[184:185] op_sel_hi:[1,0]
	v_pk_mul_f32 v[74:75], v[74:75], v[184:185] op_sel_hi:[1,0]
	v_pk_add_f32 v[98:99], v[80:81], v[80:81] op_sel_hi:[0,1]
	s_waitcnt lgkmcnt(2)
	v_pk_fma_f32 v[78:79], v[196:197], v[78:79], v[112:113]
	v_pk_fma_f32 v[80:81], v[198:199], v[76:77], v[114:115]
	s_waitcnt lgkmcnt(0)
	v_pk_fma_f32 v[76:77], v[206:207], v[74:75], v[202:203]
	v_pk_fma_f32 v[74:75], v[204:205], v[82:83], v[200:201]
	global_store_dwordx4 v180, v[78:81], s[40:41] offset:2048 sc1
	global_store_dwordx4 v180, v[74:77], s[40:41] offset:3072 sc1
	v_add_f32_e32 v113, v78, v79
	v_add_f32_e32 v115, v80, v81
	v_mov_b32_e32 v112, v74
	v_mov_b32_e32 v114, v75
	v_pk_add_f32 v[82:83], v[112:113], v[114:115]
	ds_read_b128 v[112:115], v236 offset:4096
	ds_read_b128 v[196:199], v236 offset:20480
	v_add_f32_e32 v88, v88, v89
	v_add_f32_e32 v89, 0, v88
	v_mov_b32_e32 v98, v76
	v_mov_b32_e32 v88, v77
	v_pk_mul_f32 v[70:71], v[70:71], v[184:185] op_sel_hi:[1,0]
	v_pk_mul_f32 v[72:73], v[72:73], v[184:185] op_sel_hi:[1,0]
	ds_read_b128 v[200:203], v236 offset:21504
	ds_read_b128 v[204:207], v236 offset:5120
	v_pk_add_f32 v[88:89], v[98:99], v[88:89]
	s_waitcnt lgkmcnt(2)
	v_pk_fma_f32 v[72:73], v[114:115], v[72:73], v[198:199]
	v_pk_fma_f32 v[70:71], v[112:113], v[70:71], v[196:197]
	v_pk_add_f32 v[82:83], v[82:83], v[88:89]
	v_add_co_u32_e32 v128, vcc, s46, v182
	v_pk_mov_b32 v[88:89], v[70:71], v[72:73] op_sel:[1,0]
	v_mov_b32_e32 v98, v70
	v_mov_b32_e32 v99, v73
	v_addc_co_u32_e32 v129, vcc, 0, v183, vcc
	v_pk_add_f32 v[88:89], v[88:89], v[98:99]
	v_add_co_u32_e32 v208, vcc, s45, v182
	v_pk_add_f32 v[98:99], v[88:89], v[88:89] op_sel_hi:[0,1]
	v_pk_mul_f32 v[88:89], v[186:187], v[184:185] op_sel_hi:[1,0]
	v_pk_mul_f32 v[68:69], v[68:69], v[184:185] op_sel_hi:[1,0]
	v_addc_co_u32_e32 v209, vcc, 0, v183, vcc
	s_waitcnt lgkmcnt(0)
	v_pk_fma_f32 v[114:115], v[206:207], v[68:69], v[202:203]
	v_pk_fma_f32 v[112:113], v[204:205], v[88:89], v[200:201]
	global_store_dwordx4 v[208:209], v[70:73], off offset:-4096 sc1
	global_store_dwordx4 v[128:129], v[112:115], off offset:1024 sc1
	ds_read_b128 v[186:189], v236 offset:22528
	ds_read_b128 v[196:199], v236 offset:6144
	v_pk_mul_f32 v[88:89], v[90:91], v[184:185] op_sel_hi:[1,0]
	v_pk_mul_f32 v[90:91], v[138:139], v[184:185] op_sel_hi:[1,0]
	v_pk_add_f32 v[82:83], v[82:83], v[82:83] op_sel_hi:[0,1]
	ds_read_b128 v[200:203], v236 offset:23552
	ds_read_b128 v[204:207], v236 offset:7168
	s_waitcnt lgkmcnt(2)
	v_pk_fma_f32 v[90:91], v[198:199], v[90:91], v[188:189]
	v_pk_fma_f32 v[88:89], v[196:197], v[88:89], v[186:187]
	v_add_f32_e32 v69, v112, v113
	v_add_f32_e32 v211, v114, v115
	v_mov_b32_e32 v68, v88
	v_mov_b32_e32 v210, v89
	v_mov_b32_e32 v98, v90
	v_mov_b32_e32 v82, v91
	v_pk_add_f32 v[68:69], v[68:69], v[210:211]
	v_pk_add_f32 v[82:83], v[98:99], v[82:83]
	v_pk_mul_f32 v[96:97], v[96:97], v[184:185] op_sel_hi:[1,0]
	v_pk_add_f32 v[68:69], v[68:69], v[82:83]
	s_waitcnt lgkmcnt(0)
	v_pk_fma_f32 v[98:99], v[206:207], v[96:97], v[202:203]
	v_pk_add_f32 v[82:83], v[68:69], v[68:69] op_sel_hi:[0,1]
	v_pk_mul_f32 v[68:69], v[134:135], v[184:185] op_sel_hi:[1,0]
	global_store_dwordx4 v[128:129], v[88:91], off offset:2048 sc1
	v_pk_fma_f32 v[96:97], v[204:205], v[68:69], v[200:201]
	global_store_dwordx4 v[128:129], v[96:99], off offset:3072 sc1
	ds_read_b128 v[186:189], v236 offset:8192
	ds_read_b128 v[196:199], v236 offset:24576
	ds_read_b128 v[200:203], v236 offset:25600
	ds_read_b128 v[204:207], v236 offset:9216
	v_pk_mov_b32 v[68:69], v[96:97], v[98:99] op_sel:[1,0]
	v_mov_b32_e32 v128, v96
	v_mov_b32_e32 v129, v99
	v_pk_add_f32 v[68:69], v[68:69], v[128:129]
	v_pk_mul_f32 v[66:67], v[66:67], v[184:185] op_sel_hi:[1,0]
	v_pk_add_f32 v[134:135], v[68:69], v[68:69] op_sel_hi:[0,1]
	v_pk_mul_f32 v[68:69], v[100:101], v[184:185] op_sel_hi:[1,0]
	v_pk_mul_f32 v[110:111], v[110:111], v[184:185] op_sel_hi:[1,0]
	v_pk_mul_f32 v[128:129], v[130:131], v[184:185] op_sel_hi:[1,0]
	s_waitcnt lgkmcnt(2)
	v_pk_fma_f32 v[68:69], v[188:189], v[68:69], v[198:199]
	v_pk_fma_f32 v[66:67], v[186:187], v[66:67], v[196:197]
	s_waitcnt lgkmcnt(0)
	v_pk_fma_f32 v[130:131], v[206:207], v[128:129], v[202:203]
	v_pk_fma_f32 v[128:129], v[204:205], v[110:111], v[200:201]
	global_store_dwordx4 v[208:209], v[66:69], off sc1
	global_store_dwordx4 v[208:209], v[128:131], off offset:1024 sc1
	ds_read_b128 v[186:189], v236 offset:26624
	ds_read_b128 v[196:199], v236 offset:10240
	v_add_f32_e32 v101, v66, v67
	v_add_f32_e32 v139, v68, v69
	v_mov_b32_e32 v100, v128
	v_mov_b32_e32 v138, v129
	v_mov_b32_e32 v134, v130
	v_mov_b32_e32 v82, v131
	v_pk_add_f32 v[100:101], v[100:101], v[138:139]
	v_pk_add_f32 v[82:83], v[134:135], v[82:83]
	ds_read_b128 v[200:203], v236 offset:27648
	ds_read_b128 v[204:207], v236 offset:11264
	v_pk_add_f32 v[82:83], v[100:101], v[82:83]
	v_pk_mul_f32 v[100:101], v[106:107], v[184:185] op_sel_hi:[1,0]
	v_pk_mul_f32 v[106:107], v[108:109], v[184:185] op_sel_hi:[1,0]
	v_pk_mul_f32 v[122:123], v[122:123], v[184:185] op_sel_hi:[1,0]
	s_waitcnt lgkmcnt(2)
	v_pk_fma_f32 v[108:109], v[106:107], v[198:199], v[188:189]
	v_pk_fma_f32 v[106:107], v[100:101], v[196:197], v[186:187]
	v_mov_b32_e32 v111, v109
	v_pk_mov_b32 v[100:101], v[106:107], v[108:109] op_sel:[1,0]
	v_mov_b32_e32 v110, v106
	v_pk_add_f32 v[100:101], v[100:101], v[110:111]
	global_store_dwordx4 v[208:209], v[106:109], off offset:2048 sc1
	v_pk_add_f32 v[110:111], v[100:101], v[100:101] op_sel_hi:[0,1]
	v_pk_mul_f32 v[100:101], v[102:103], v[184:185] op_sel_hi:[1,0]
	v_pk_mul_f32 v[102:103], v[104:105], v[184:185] op_sel_hi:[1,0]
	s_waitcnt lgkmcnt(0)
	v_pk_fma_f32 v[100:101], v[100:101], v[204:205], v[200:201]
	v_pk_fma_f32 v[102:103], v[102:103], v[206:207], v[202:203]
	global_store_dwordx4 v[208:209], v[100:103], off offset:3072 sc1
	ds_read_b128 v[186:189], v236 offset:12288
	ds_read_b128 v[196:199], v236 offset:28672
	v_pk_mul_f32 v[132:133], v[132:133], v[184:185] op_sel_hi:[1,0]
	ds_read_b128 v[200:203], v236 offset:29696
	ds_read_b128 v[204:207], v236 offset:13312
	v_pk_add_f32 v[82:83], v[82:83], v[82:83] op_sel_hi:[0,1]
	v_add_f32_e32 v105, v100, v101
	s_waitcnt lgkmcnt(2)
	v_pk_fma_f32 v[134:135], v[132:133], v[188:189], v[198:199]
	v_pk_fma_f32 v[132:133], v[122:123], v[186:187], v[196:197]
	v_add_f32_e32 v139, v102, v103
	v_mov_b32_e32 v104, v132
	v_mov_b32_e32 v138, v133
	v_mov_b32_e32 v110, v134
	v_mov_b32_e32 v82, v135
	v_pk_add_f32 v[104:105], v[104:105], v[138:139]
	v_pk_add_f32 v[82:83], v[110:111], v[82:83]
	v_pk_mul_f32 v[110:111], v[116:117], v[184:185] op_sel_hi:[1,0]
	v_pk_add_f32 v[82:83], v[104:105], v[82:83]
	v_pk_mul_f32 v[104:105], v[136:137], v[184:185] op_sel_hi:[1,0]
	ds_read_b128 v[186:189], v236 offset:30720
	ds_read_b128 v[196:199], v236 offset:14336
	s_waitcnt lgkmcnt(2)
	v_pk_fma_f32 v[138:139], v[110:111], v[206:207], v[202:203]
	v_pk_fma_f32 v[136:137], v[104:105], v[204:205], v[200:201]
	ds_read_b128 v[200:203], v236 offset:31744
	ds_read_b128 v[204:207], v236 offset:15360
	v_pk_mov_b32 v[104:105], v[136:137], v[138:139] op_sel:[1,0]
	v_mov_b32_e32 v110, v136
	v_mov_b32_e32 v111, v139
	v_pk_mul_f32 v[116:117], v[120:121], v[184:185] op_sel_hi:[1,0]
	v_pk_add_f32 v[104:105], v[104:105], v[110:111]
	v_pk_mul_f32 v[110:111], v[124:125], v[184:185] op_sel_hi:[1,0]
	s_waitcnt lgkmcnt(2)
	v_pk_fma_f32 v[122:123], v[116:117], v[198:199], v[188:189]
	v_pk_mul_f32 v[116:117], v[126:127], v[184:185] op_sel_hi:[1,0]
	v_pk_mul_f32 v[118:119], v[118:119], v[184:185] op_sel_hi:[1,0]
	v_pk_add_f32 v[82:83], v[82:83], v[82:83] op_sel:[0,1] op_sel_hi:[1,0]
	v_pk_add_f32 v[104:105], v[104:105], v[104:105] op_sel:[0,1] op_sel_hi:[1,0]
	v_pk_fma_f32 v[120:121], v[110:111], v[196:197], v[186:187]
	s_waitcnt lgkmcnt(0)
	v_pk_fma_f32 v[118:119], v[118:119], v[206:207], v[202:203]
	v_pk_fma_f32 v[116:117], v[116:117], v[204:205], v[200:201]
	v_add_f32_e32 v110, v120, v121
	v_add_f32_e32 v124, v122, v123
	v_mov_b32_e32 v105, v116
	v_mov_b32_e32 v83, v117
	v_mov_b32_e32 v111, v118
	v_mov_b32_e32 v125, v119
	v_pk_add_f32 v[82:83], v[104:105], v[82:83]
	v_pk_add_f32 v[104:105], v[110:111], v[124:125]
	s_nop 0
	v_pk_add_f32 v[82:83], v[82:83], v[104:105]
	s_nop 0
	v_add_f32_e32 v82, v82, v83
	ds_bpermute_b32 v83, v185, v82
	s_waitcnt lgkmcnt(0)
	v_add_f32_e32 v82, v82, v83
	ds_bpermute_b32 v83, v190, v82
	s_waitcnt lgkmcnt(0)
	v_add_f32_e32 v82, v82, v83
	ds_bpermute_b32 v83, v191, v82
	s_waitcnt lgkmcnt(0)
	v_add_f32_e32 v82, v82, v83
	ds_bpermute_b32 v83, v192, v82
	s_waitcnt lgkmcnt(0)
	v_add_f32_e32 v104, v82, v83
	ds_bpermute_b32 v105, v193, v104
	v_add_co_u32_e32 v82, vcc, s47, v182
	s_waitcnt lgkmcnt(0)
	v_add_f32_e32 v104, v104, v105
	ds_bpermute_b32 v105, v194, v104
	v_addc_co_u32_e32 v83, vcc, 0, v183, vcc
	global_store_dwordx4 v[82:83], v[132:135], off sc1
	global_store_dwordx4 v[82:83], v[136:139], off offset:1024 sc1
	global_store_dwordx4 v[82:83], v[120:123], off offset:2048 sc1
	global_store_dwordx4 v[82:83], v[116:119], off offset:3072 sc1
	s_waitcnt lgkmcnt(0)
	v_add_f32_e32 v126, v104, v105
	v_fmamk_f32 v85, v126, 0xb9800000, v85
	v_fmac_f32_e32 v84, 0xb9800000, v126
	v_fmamk_f32 v87, v126, 0xb9800000, v87
	v_fmac_f32_e32 v86, 0xb9800000, v126
	v_pk_mul_f32 v[82:83], v[86:87], v[86:87]
	v_pk_mul_f32 v[104:105], v[84:85], v[84:85]
	v_fmamk_f32 v93, v126, 0xb9800000, v93
	v_pk_mov_b32 v[110:111], v[104:105], v[82:83] op_sel:[1,0]
	v_mov_b32_e32 v105, v83
	v_pk_add_f32 v[82:83], v[110:111], v[104:105]
	v_fmac_f32_e32 v92, 0xb9800000, v126
	v_fmamk_f32 v95, v126, 0xb9800000, v95
	v_fmac_f32_e32 v94, 0xb9800000, v126
	v_pk_add_f32 v[82:83], v[82:83], v[82:83] op_sel_hi:[0,1]
	v_pk_mul_f32 v[104:105], v[94:95], v[94:95]
	v_pk_mul_f32 v[110:111], v[92:93], v[92:93]
	v_fmac_f32_e32 v78, 0xb9800000, v126
	v_pk_mov_b32 v[124:125], v[110:111], v[104:105] op_sel:[1,0]
	v_mov_b32_e32 v111, v105
	v_fmamk_f32 v79, v126, 0xb9800000, v79
	v_fmac_f32_e32 v80, 0xb9800000, v126
	v_mul_f32_e32 v82, v78, v78
	v_pk_add_f32 v[104:105], v[124:125], v[110:111]
	v_fmamk_f32 v81, v126, 0xb9800000, v81
	v_pk_fma_f32 v[110:111], v[78:79], v[78:79], v[82:83] op_sel_hi:[1,1,0]
	v_mul_f32_e32 v82, v80, v80
	v_pk_add_f32 v[104:105], v[104:105], v[104:105] op_sel_hi:[0,1]
	v_pk_fma_f32 v[124:125], v[80:81], v[80:81], v[82:83] op_sel_hi:[1,1,0]
	v_fmamk_f32 v77, v126, 0xb9800000, v77
	v_fmac_f32_e32 v76, 0xb9800000, v126
	v_fmamk_f32 v75, v126, 0xb9800000, v75
	v_fmac_f32_e32 v74, 0xb9800000, v126
	v_mul_f32_e32 v110, v74, v74
	v_mul_f32_e32 v124, v75, v75
	v_mul_f32_e32 v82, v76, v76
	v_mul_f32_e32 v104, v77, v77
	v_pk_add_f32 v[110:111], v[110:111], v[124:125]
	v_pk_add_f32 v[82:83], v[82:83], v[104:105]
	v_fmamk_f32 v71, v126, 0xb9800000, v71
	v_pk_add_f32 v[82:83], v[110:111], v[82:83]
	v_fmac_f32_e32 v70, 0xb9800000, v126
	v_fmamk_f32 v73, v126, 0xb9800000, v73
	v_fmac_f32_e32 v72, 0xb9800000, v126
	v_pk_add_f32 v[82:83], v[82:83], v[82:83] op_sel_hi:[0,1]
	v_pk_mul_f32 v[104:105], v[72:73], v[72:73]
	v_pk_mul_f32 v[110:111], v[70:71], v[70:71]
	v_fmac_f32_e32 v112, 0xb9800000, v126
	v_pk_mov_b32 v[124:125], v[110:111], v[104:105] op_sel:[1,0]
	v_mov_b32_e32 v111, v105
	v_fmamk_f32 v113, v126, 0xb9800000, v113
	v_fmac_f32_e32 v114, 0xb9800000, v126
	v_mul_f32_e32 v82, v112, v112
	v_pk_add_f32 v[104:105], v[124:125], v[110:111]
	v_fmamk_f32 v115, v126, 0xb9800000, v115
	v_pk_fma_f32 v[110:111], v[112:113], v[112:113], v[82:83] op_sel_hi:[1,1,0]
	v_mul_f32_e32 v82, v114, v114
	v_pk_add_f32 v[104:105], v[104:105], v[104:105] op_sel_hi:[0,1]
	v_pk_fma_f32 v[124:125], v[114:115], v[114:115], v[82:83] op_sel_hi:[1,1,0]
	v_fmamk_f32 v91, v126, 0xb9800000, v91
	v_fmac_f32_e32 v90, 0xb9800000, v126
	v_fmamk_f32 v89, v126, 0xb9800000, v89
	v_fmac_f32_e32 v88, 0xb9800000, v126
	v_mul_f32_e32 v110, v88, v88
	v_mul_f32_e32 v124, v89, v89
	v_mul_f32_e32 v104, v90, v90
	v_mul_f32_e32 v82, v91, v91
	v_pk_add_f32 v[110:111], v[110:111], v[124:125]
	v_pk_add_f32 v[82:83], v[104:105], v[82:83]
	v_fmamk_f32 v97, v126, 0xb9800000, v97
	v_pk_add_f32 v[82:83], v[110:111], v[82:83]
	v_fmac_f32_e32 v96, 0xb9800000, v126
	v_fmamk_f32 v99, v126, 0xb9800000, v99
	v_fmac_f32_e32 v98, 0xb9800000, v126
	v_pk_add_f32 v[82:83], v[82:83], v[82:83] op_sel_hi:[0,1]
	v_pk_mul_f32 v[104:105], v[98:99], v[98:99]
	v_pk_mul_f32 v[110:111], v[96:97], v[96:97]
	v_fmac_f32_e32 v66, 0xb9800000, v126
	v_pk_mov_b32 v[124:125], v[110:111], v[104:105] op_sel:[1,0]
	v_mov_b32_e32 v111, v105
	v_fmamk_f32 v67, v126, 0xb9800000, v67
	v_fmac_f32_e32 v68, 0xb9800000, v126
	v_mul_f32_e32 v82, v66, v66
	v_pk_add_f32 v[104:105], v[124:125], v[110:111]
	v_fmamk_f32 v69, v126, 0xb9800000, v69
	v_pk_fma_f32 v[110:111], v[66:67], v[66:67], v[82:83] op_sel_hi:[1,1,0]
	v_mul_f32_e32 v82, v68, v68
	v_pk_add_f32 v[104:105], v[104:105], v[104:105] op_sel_hi:[0,1]
	v_pk_fma_f32 v[124:125], v[68:69], v[68:69], v[82:83] op_sel_hi:[1,1,0]
	v_fmamk_f32 v131, v126, 0xb9800000, v131
	v_fmac_f32_e32 v130, 0xb9800000, v126
	v_fmamk_f32 v129, v126, 0xb9800000, v129
	v_fmac_f32_e32 v128, 0xb9800000, v126
	v_mul_f32_e32 v110, v128, v128
	v_mul_f32_e32 v124, v129, v129
	v_mul_f32_e32 v104, v130, v130
	v_mul_f32_e32 v82, v131, v131
	v_pk_add_f32 v[110:111], v[110:111], v[124:125]
	v_pk_add_f32 v[82:83], v[104:105], v[82:83]
	v_fmamk_f32 v107, v126, 0xb9800000, v107
	v_pk_add_f32 v[82:83], v[110:111], v[82:83]
	v_fmac_f32_e32 v106, 0xb9800000, v126
	v_fmamk_f32 v109, v126, 0xb9800000, v109
	v_fmac_f32_e32 v108, 0xb9800000, v126
	v_pk_add_f32 v[82:83], v[82:83], v[82:83] op_sel_hi:[0,1]
	v_pk_mul_f32 v[104:105], v[108:109], v[108:109]
	v_pk_mul_f32 v[110:111], v[106:107], v[106:107]
	v_fmac_f32_e32 v100, 0xb9800000, v126
	v_pk_mov_b32 v[124:125], v[110:111], v[104:105] op_sel:[1,0]
	v_mov_b32_e32 v111, v105
	v_fmamk_f32 v101, v126, 0xb9800000, v101
	v_fmac_f32_e32 v102, 0xb9800000, v126
	v_mul_f32_e32 v82, v100, v100
	v_pk_add_f32 v[104:105], v[124:125], v[110:111]
	v_fmamk_f32 v103, v126, 0xb9800000, v103
	v_pk_fma_f32 v[110:111], v[100:101], v[100:101], v[82:83] op_sel_hi:[1,1,0]
	v_mul_f32_e32 v82, v102, v102
	v_pk_add_f32 v[104:105], v[104:105], v[104:105] op_sel_hi:[0,1]
	v_pk_fma_f32 v[124:125], v[102:103], v[102:103], v[82:83] op_sel_hi:[1,1,0]
	v_fmamk_f32 v135, v126, 0xb9800000, v135
	v_fmac_f32_e32 v134, 0xb9800000, v126
	v_fmamk_f32 v133, v126, 0xb9800000, v133
	v_fmac_f32_e32 v132, 0xb9800000, v126
	v_mul_f32_e32 v110, v132, v132
	v_mul_f32_e32 v124, v133, v133
	v_mul_f32_e32 v104, v134, v134
	v_mul_f32_e32 v82, v135, v135
	v_pk_add_f32 v[110:111], v[110:111], v[124:125]
	v_pk_add_f32 v[82:83], v[104:105], v[82:83]
	v_fmamk_f32 v137, v126, 0xb9800000, v137
	v_pk_add_f32 v[82:83], v[110:111], v[82:83]
	v_fmac_f32_e32 v136, 0xb9800000, v126
	v_fmamk_f32 v139, v126, 0xb9800000, v139
	v_fmac_f32_e32 v138, 0xb9800000, v126
	v_pk_add_f32 v[82:83], v[82:83], v[82:83] op_sel_hi:[0,1]
	v_pk_mul_f32 v[104:105], v[138:139], v[138:139]
	v_pk_mul_f32 v[110:111], v[136:137], v[136:137]
	v_fmac_f32_e32 v120, 0xb9800000, v126
	v_pk_mov_b32 v[124:125], v[110:111], v[104:105] op_sel:[1,0]
	v_mov_b32_e32 v111, v105
	v_fmamk_f32 v121, v126, 0xb9800000, v121
	v_fmac_f32_e32 v122, 0xb9800000, v126
	v_mul_f32_e32 v82, v120, v120
	v_pk_add_f32 v[104:105], v[124:125], v[110:111]
	v_fmamk_f32 v123, v126, 0xb9800000, v123
	v_pk_fma_f32 v[110:111], v[120:121], v[120:121], v[82:83] op_sel_hi:[1,1,0]
	v_mul_f32_e32 v82, v122, v122
	v_pk_add_f32 v[104:105], v[104:105], v[104:105] op_sel_hi:[0,1]
	v_pk_fma_f32 v[124:125], v[122:123], v[122:123], v[82:83] op_sel_hi:[1,1,0]
	v_fmamk_f32 v119, v126, 0xb9800000, v119
	v_fmac_f32_e32 v118, 0xb9800000, v126
	v_fmamk_f32 v117, v126, 0xb9800000, v117
	v_fmac_f32_e32 v116, 0xb9800000, v126
	v_mul_f32_e32 v110, v116, v116
	v_mul_f32_e32 v124, v117, v117
	v_mul_f32_e32 v104, v118, v118
	v_mul_f32_e32 v82, v119, v119
	v_pk_add_f32 v[110:111], v[110:111], v[124:125]
	v_pk_add_f32 v[82:83], v[104:105], v[82:83]
	s_nop 0
	v_pk_add_f32 v[82:83], v[110:111], v[82:83]
	s_nop 0
	v_add_f32_e32 v82, v82, v83
	ds_bpermute_b32 v83, v185, v82
	s_waitcnt lgkmcnt(0)
	v_add_f32_e32 v82, v82, v83
	ds_bpermute_b32 v83, v190, v82
	s_waitcnt lgkmcnt(0)
	v_add_f32_e32 v82, v82, v83
	ds_bpermute_b32 v83, v191, v82
	s_waitcnt lgkmcnt(0)
	v_add_f32_e32 v82, v82, v83
	ds_bpermute_b32 v83, v192, v82
	s_waitcnt lgkmcnt(0)
	v_add_f32_e32 v82, v82, v83
	ds_bpermute_b32 v83, v193, v82
	s_waitcnt lgkmcnt(0)
	v_add_f32_e32 v82, v82, v83
	ds_bpermute_b32 v83, v194, v82
	s_waitcnt lgkmcnt(0)
	v_add_f32_e32 v82, v82, v83
	v_fmamk_f32 v82, v82, 0x39800000, v179
	v_mul_f32_e32 v83, 0x4f800000, v82
	v_cmp_gt_f32_e32 vcc, s48, v82
	s_nop 1
	v_cndmask_b32_e32 v82, v82, v83, vcc
	v_sqrt_f32_e32 v83, v82
	s_nop 0
	v_add_u32_e32 v104, -1, v83
	v_fma_f32 v105, -v104, v83, v82
	v_cmp_ge_f32_e64 s[0:1], 0, v105
	v_add_u32_e32 v105, 1, v83
	s_nop 0
	v_cndmask_b32_e64 v104, v83, v104, s[0:1]
	v_fma_f32 v83, -v105, v83, v82
	v_cmp_lt_f32_e64 s[0:1], 0, v83
	s_nop 1
	v_cndmask_b32_e64 v83, v104, v105, s[0:1]
	v_mul_f32_e32 v104, 0x37800000, v83
	v_cndmask_b32_e32 v83, v83, v104, vcc
	v_cmp_class_f32_e32 vcc, v82, v237
	s_nop 1
	v_cndmask_b32_e32 v82, v83, v82, vcc
	v_div_scale_f32 v83, s[0:1], v82, v82, 1.0
	v_rcp_f32_e32 v104, v83
	s_lshl_b64 s[0:1], s[24:25], 12
	s_and_b64 s[24:25], s[26:27], exec
	s_cselect_b32 s2, 0, s2
	v_fma_f32 v105, -v83, v104, 1.0
	v_fmac_f32_e32 v104, v105, v104
	v_div_scale_f32 v105, vcc, 1.0, v82, 1.0
	v_mul_f32_e32 v110, v105, v104
	v_fma_f32 v111, -v83, v110, v105
	v_fmac_f32_e32 v110, v111, v104
	v_fma_f32 v83, -v83, v110, v105
	v_div_fmas_f32 v83, v83, v104, v110
	v_div_fixup_f32 v82, v83, v82, 1.0
	v_add_u32_e32 v83, s2, v236
	ds_read_b128 v[124:127], v83 offset:49152
	ds_read_b128 v[186:189], v83 offset:50176
	ds_read_b128 v[182:185], v83 offset:32768
	ds_read_b128 v[190:193], v83 offset:33792
	v_pk_mul_f32 v[84:85], v[84:85], v[82:83] op_sel_hi:[1,0]
	s_waitcnt lgkmcnt(3)
	v_pk_add_f32 v[110:111], v[124:125], 1.0 op_sel_hi:[1,0]
	v_pk_mul_f32 v[78:79], v[78:79], v[82:83] op_sel_hi:[1,0]
	s_waitcnt lgkmcnt(1)
	v_pk_fma_f32 v[84:85], v[110:111], v[84:85], v[182:183]
	v_mov_b32_e32 v110, v181
	v_cvt_pk_fp8_f32 v110, v84, v85
	v_pk_mul_f32 v[84:85], v[86:87], v[82:83] op_sel_hi:[1,0]
	v_pk_add_f32 v[86:87], v[126:127], 1.0 op_sel_hi:[1,0]
	v_mov_b32_e32 v111, v181
	v_pk_fma_f32 v[84:85], v[86:87], v[84:85], v[184:185]
	v_pk_mul_f32 v[86:87], v[94:95], v[82:83] op_sel_hi:[1,0]
	v_cvt_pk_fp8_f32 v110, v84, v85 op_sel:[0,0,1]
	v_pk_mul_f32 v[84:85], v[92:93], v[82:83] op_sel_hi:[1,0]
	v_pk_add_f32 v[92:93], v[186:187], 1.0 op_sel_hi:[1,0]
	ds_read_b128 v[124:127], v83 offset:52224
	s_waitcnt lgkmcnt(1)
	v_pk_fma_f32 v[84:85], v[92:93], v[84:85], v[190:191]
	ds_read_b128 v[182:185], v83 offset:35840
	v_cvt_pk_fp8_f32 v111, v84, v85
	v_pk_add_f32 v[84:85], v[188:189], 1.0 op_sel_hi:[1,0]
	v_pk_mul_f32 v[74:75], v[74:75], v[82:83] op_sel_hi:[1,0]
	v_pk_fma_f32 v[92:93], v[84:85], v[86:87], v[192:193]
	ds_read_b128 v[84:87], v83 offset:51200
	v_cvt_pk_fp8_f32 v111, v92, v93 op_sel:[0,0,1]
	ds_read_b128 v[92:95], v83 offset:34816
	v_lshl_add_u64 v[104:105], v[176:177], 0, s[0:1]
	v_pk_mul_f32 v[70:71], v[70:71], v[82:83] op_sel_hi:[1,0]
	s_waitcnt lgkmcnt(1)
	v_pk_add_f32 v[84:85], v[84:85], 1.0 op_sel_hi:[1,0]
	v_pk_mul_f32 v[88:89], v[88:89], v[82:83] op_sel_hi:[1,0]
	s_waitcnt lgkmcnt(0)
	v_pk_fma_f32 v[78:79], v[84:85], v[78:79], v[92:93]
	v_mov_b32_e32 v84, v181
	v_cvt_pk_fp8_f32 v84, v78, v79
	v_pk_mul_f32 v[78:79], v[80:81], v[82:83] op_sel_hi:[1,0]
	v_pk_add_f32 v[80:81], v[86:87], 1.0 op_sel_hi:[1,0]
	v_pk_mul_f32 v[66:67], v[66:67], v[82:83] op_sel_hi:[1,0]
	v_pk_fma_f32 v[78:79], v[80:81], v[78:79], v[94:95]
	s_add_u32 s14, s14, s34
	v_cvt_pk_fp8_f32 v84, v78, v79 op_sel:[0,0,1]
	v_pk_add_f32 v[78:79], v[124:125], 1.0 op_sel_hi:[1,0]
	s_addc_u32 s15, s15, s35
	v_pk_fma_f32 v[74:75], v[78:79], v[74:75], v[182:183]
	v_mov_b32_e32 v78, v181
	v_cvt_pk_fp8_f32 v78, v74, v75
	v_pk_mul_f32 v[74:75], v[76:77], v[82:83] op_sel_hi:[1,0]
	v_pk_add_f32 v[76:77], v[126:127], 1.0 op_sel_hi:[1,0]
	s_add_u32 s4, s4, s6
	v_pk_fma_f32 v[74:75], v[76:77], v[74:75], v[184:185]
	s_addc_u32 s5, s5, s7
	v_cvt_pk_fp8_f32 v78, v74, v75 op_sel:[0,0,1]
	global_store_dword v[104:105], v110, off
	global_store_dword v[104:105], v111, off offset:256
	global_store_dword v[104:105], v84, off offset:512
	global_store_dword v[104:105], v78, off offset:768
	ds_read_b128 v[74:77], v83 offset:53248
	ds_read_b128 v[78:81], v83 offset:36864
	ds_read_b128 v[84:87], v83 offset:54272
	ds_read_b128 v[92:95], v83 offset:37888
	v_mov_b32_e32 v110, v181
	s_waitcnt lgkmcnt(3)
	v_pk_add_f32 v[74:75], v[74:75], 1.0 op_sel_hi:[1,0]
	s_add_i32 s19, s19, s44
	s_waitcnt lgkmcnt(2)
	v_pk_fma_f32 v[70:71], v[74:75], v[70:71], v[78:79]
	s_waitcnt lgkmcnt(1)
	v_pk_add_f32 v[74:75], v[84:85], 1.0 op_sel_hi:[1,0]
	v_cvt_pk_fp8_f32 v110, v70, v71
	v_pk_mul_f32 v[70:71], v[72:73], v[82:83] op_sel_hi:[1,0]
	v_pk_add_f32 v[72:73], v[76:77], 1.0 op_sel_hi:[1,0]
	s_andn2_b64 vcc, exec, s[38:39]
	v_pk_fma_f32 v[70:71], v[72:73], v[70:71], v[80:81]
	v_pk_mul_f32 v[72:73], v[114:115], v[82:83] op_sel_hi:[1,0]
	v_cvt_pk_fp8_f32 v110, v70, v71 op_sel:[0,0,1]
	v_pk_mul_f32 v[70:71], v[112:113], v[82:83] op_sel_hi:[1,0]
	ds_read_b128 v[78:81], v83 offset:56320
	s_waitcnt lgkmcnt(1)
	v_pk_fma_f32 v[70:71], v[74:75], v[70:71], v[92:93]
	v_mov_b32_e32 v92, v181
	v_cvt_pk_fp8_f32 v92, v70, v71
	v_pk_add_f32 v[70:71], v[86:87], 1.0 op_sel_hi:[1,0]
	ds_read_b128 v[84:87], v83 offset:39936
	v_pk_fma_f32 v[74:75], v[70:71], v[72:73], v[94:95]
	ds_read_b128 v[70:73], v83 offset:55296
	v_cvt_pk_fp8_f32 v92, v74, v75 op_sel:[0,0,1]
	ds_read_b128 v[74:77], v83 offset:38912
	s_mov_b32 s24, s36
	s_waitcnt lgkmcnt(1)
	v_pk_add_f32 v[70:71], v[70:71], 1.0 op_sel_hi:[1,0]
	v_pk_add_f32 v[72:73], v[72:73], 1.0 op_sel_hi:[1,0]
	s_waitcnt lgkmcnt(0)
	v_pk_fma_f32 v[70:71], v[88:89], v[70:71], v[74:75]
	v_mov_b32_e32 v74, v181
	v_cvt_pk_fp8_f32 v74, v70, v71
	v_pk_mul_f32 v[70:71], v[90:91], v[82:83] op_sel_hi:[1,0]
	v_mov_b32_e32 v75, v181
	v_pk_fma_f32 v[70:71], v[70:71], v[72:73], v[76:77]
	v_pk_add_f32 v[72:73], v[78:79], 1.0 op_sel_hi:[1,0]
	v_cvt_pk_fp8_f32 v74, v70, v71 op_sel:[0,0,1]
	v_pk_mul_f32 v[70:71], v[96:97], v[82:83] op_sel_hi:[1,0]
	v_mov_b32_e32 v88, v181
	v_pk_fma_f32 v[70:71], v[70:71], v[72:73], v[84:85]
	v_pk_add_f32 v[72:73], v[80:81], 1.0 op_sel_hi:[1,0]
	v_cvt_pk_fp8_f32 v75, v70, v71
	v_pk_mul_f32 v[70:71], v[98:99], v[82:83] op_sel_hi:[1,0]
	v_mov_b32_e32 v89, v181
	v_pk_fma_f32 v[70:71], v[70:71], v[72:73], v[86:87]
	s_nop 0
	v_cvt_pk_fp8_f32 v75, v70, v71 op_sel:[0,0,1]
	global_store_dword v[104:105], v110, off offset:1024
	global_store_dword v[104:105], v92, off offset:1280
	global_store_dword v[104:105], v74, off offset:1536
	global_store_dword v[104:105], v75, off offset:1792
	ds_read_b128 v[70:73], v83 offset:57344
	ds_read_b128 v[74:77], v83 offset:40960
	ds_read_b128 v[78:81], v83 offset:58368
	ds_read_b128 v[84:87], v83 offset:41984
	s_waitcnt lgkmcnt(3)
	v_pk_add_f32 v[70:71], v[70:71], 1.0 op_sel_hi:[1,0]
	s_waitcnt lgkmcnt(2)
	v_pk_fma_f32 v[66:67], v[66:67], v[70:71], v[74:75]
	s_waitcnt lgkmcnt(1)
	v_pk_add_f32 v[70:71], v[78:79], 1.0 op_sel_hi:[1,0]
	v_cvt_pk_fp8_f32 v88, v66, v67
	v_pk_mul_f32 v[66:67], v[68:69], v[82:83] op_sel_hi:[1,0]
	v_pk_add_f32 v[68:69], v[72:73], 1.0 op_sel_hi:[1,0]
	s_nop 0
	v_pk_fma_f32 v[66:67], v[66:67], v[68:69], v[76:77]
	v_pk_mul_f32 v[68:69], v[130:131], v[82:83] op_sel_hi:[1,0]
	v_cvt_pk_fp8_f32 v88, v66, v67 op_sel:[0,0,1]
	v_pk_mul_f32 v[66:67], v[128:129], v[82:83] op_sel_hi:[1,0]
	ds_read_b128 v[74:77], v83 offset:60416
	s_waitcnt lgkmcnt(1)
	v_pk_fma_f32 v[66:67], v[66:67], v[70:71], v[84:85]
	v_pk_mul_f32 v[84:85], v[106:107], v[82:83] op_sel_hi:[1,0]
	v_cvt_pk_fp8_f32 v89, v66, v67
	v_pk_add_f32 v[66:67], v[80:81], 1.0 op_sel_hi:[1,0]
	ds_read_b128 v[78:81], v83 offset:44032
	v_pk_fma_f32 v[70:71], v[68:69], v[66:67], v[86:87]
	ds_read_b128 v[66:69], v83 offset:59392
	v_cvt_pk_fp8_f32 v89, v70, v71 op_sel:[0,0,1]
	ds_read_b128 v[70:73], v83 offset:43008
	v_mov_b32_e32 v86, v181
	v_mov_b32_e32 v87, v181
	s_waitcnt lgkmcnt(1)
	v_pk_add_f32 v[66:67], v[66:67], 1.0 op_sel_hi:[1,0]
	v_pk_add_f32 v[68:69], v[68:69], 1.0 op_sel_hi:[1,0]
	s_waitcnt lgkmcnt(0)
	v_pk_fma_f32 v[66:67], v[84:85], v[66:67], v[70:71]
	v_mov_b32_e32 v70, v181
	v_cvt_pk_fp8_f32 v70, v66, v67
	v_pk_mul_f32 v[66:67], v[108:109], v[82:83] op_sel_hi:[1,0]
	v_mov_b32_e32 v71, v181
	v_pk_fma_f32 v[66:67], v[66:67], v[68:69], v[72:73]
	v_pk_add_f32 v[68:69], v[74:75], 1.0 op_sel_hi:[1,0]
	v_cvt_pk_fp8_f32 v70, v66, v67 op_sel:[0,0,1]
	v_pk_mul_f32 v[66:67], v[100:101], v[82:83] op_sel_hi:[1,0]
	v_pk_mul_f32 v[84:85], v[132:133], v[82:83] op_sel_hi:[1,0]
	v_pk_fma_f32 v[66:67], v[66:67], v[68:69], v[78:79]
	v_pk_add_f32 v[68:69], v[76:77], 1.0 op_sel_hi:[1,0]
	v_cvt_pk_fp8_f32 v71, v66, v67
	v_pk_mul_f32 v[66:67], v[102:103], v[82:83] op_sel_hi:[1,0]
	s_nop 0
	v_pk_fma_f32 v[66:67], v[66:67], v[68:69], v[80:81]
	s_nop 0
	v_cvt_pk_fp8_f32 v71, v66, v67 op_sel:[0,0,1]
	global_store_dword v[104:105], v88, off offset:2048
	global_store_dword v[104:105], v89, off offset:2304
	global_store_dword v[104:105], v70, off offset:2560
	global_store_dword v[104:105], v71, off offset:2816
	ds_read_b128 v[66:69], v83 offset:61440
	ds_read_b128 v[70:73], v83 offset:45056
	ds_read_b128 v[74:77], v83 offset:62464
	ds_read_b128 v[78:81], v83 offset:46080
	s_waitcnt lgkmcnt(3)
	v_pk_add_f32 v[66:67], v[66:67], 1.0 op_sel_hi:[1,0]
	s_waitcnt lgkmcnt(2)
	v_pk_fma_f32 v[66:67], v[84:85], v[66:67], v[70:71]
	v_pk_add_f32 v[68:69], v[68:69], 1.0 op_sel_hi:[1,0]
	v_cvt_pk_fp8_f32 v86, v66, v67
	v_pk_mul_f32 v[66:67], v[134:135], v[82:83] op_sel_hi:[1,0]
	s_waitcnt lgkmcnt(1)
	v_pk_add_f32 v[70:71], v[74:75], 1.0 op_sel_hi:[1,0]
	v_pk_fma_f32 v[66:67], v[66:67], v[68:69], v[72:73]
	v_pk_mul_f32 v[68:69], v[138:139], v[82:83] op_sel_hi:[1,0]
	v_cvt_pk_fp8_f32 v86, v66, v67 op_sel:[0,0,1]
	v_pk_mul_f32 v[66:67], v[136:137], v[82:83] op_sel_hi:[1,0]
	v_pk_mul_f32 v[84:85], v[120:121], v[82:83] op_sel_hi:[1,0]
	s_waitcnt lgkmcnt(0)
	v_pk_fma_f32 v[66:67], v[66:67], v[70:71], v[78:79]
	s_nop 0
	v_cvt_pk_fp8_f32 v87, v66, v67
	v_pk_add_f32 v[66:67], v[76:77], 1.0 op_sel_hi:[1,0]
	ds_read_b128 v[74:77], v83 offset:64512
	v_pk_fma_f32 v[70:71], v[68:69], v[66:67], v[80:81]
	ds_read_b128 v[66:69], v83 offset:63488
	v_cvt_pk_fp8_f32 v87, v70, v71 op_sel:[0,0,1]
	ds_read_b128 v[70:73], v83 offset:47104
	ds_read_b128 v[78:81], v83 offset:48128
	s_waitcnt lgkmcnt(2)
	v_pk_add_f32 v[66:67], v[66:67], 1.0 op_sel_hi:[1,0]
	v_pk_add_f32 v[68:69], v[68:69], 1.0 op_sel_hi:[1,0]
	s_waitcnt lgkmcnt(1)
	v_pk_fma_f32 v[66:67], v[84:85], v[66:67], v[70:71]
	v_mov_b32_e32 v70, v181
	v_cvt_pk_fp8_f32 v70, v66, v67
	v_pk_mul_f32 v[66:67], v[122:123], v[82:83] op_sel_hi:[1,0]
	v_mov_b32_e32 v71, v181
	v_pk_fma_f32 v[66:67], v[66:67], v[68:69], v[72:73]
	v_pk_add_f32 v[68:69], v[74:75], 1.0 op_sel_hi:[1,0]
	v_cvt_pk_fp8_f32 v70, v66, v67 op_sel:[0,0,1]
	v_pk_mul_f32 v[66:67], v[116:117], v[82:83] op_sel_hi:[1,0]
	s_waitcnt lgkmcnt(0)
	v_pk_fma_f32 v[66:67], v[66:67], v[68:69], v[78:79]
	v_pk_add_f32 v[68:69], v[76:77], 1.0 op_sel_hi:[1,0]
	v_cvt_pk_fp8_f32 v71, v66, v67
	v_pk_mul_f32 v[66:67], v[118:119], v[82:83] op_sel_hi:[1,0]
	s_nop 0
	v_pk_fma_f32 v[66:67], v[66:67], v[68:69], v[80:81]
	s_nop 0
	v_cvt_pk_fp8_f32 v71, v66, v67 op_sel:[0,0,1]
	global_store_dword v[104:105], v86, off offset:3072
	global_store_dword v[104:105], v87, off offset:3328
	global_store_dword v[104:105], v70, off offset:3584
	global_store_dword v[104:105], v71, off offset:3840
	s_cbranch_vccz .LBB0_883

.LBB0_1111:
	v_add_f32_e32 v164, v126, v127
	v_add_f32_e32 v165, v128, v129
	v_add_f32_e32 v164, v164, v165
	v_and_b32_e32 v165, 64, v233
	v_add_u32_e32 v165, 64, v165
	v_xor_b32_e32 v166, 1, v233
	v_cmp_lt_i32_e32 vcc, v166, v165
	v_add_f32_e32 v164, v234, v164
	s_add_u32 s6, s60, s34
	v_cndmask_b32_e32 v166, v233, v166, vcc
	v_lshlrev_b32_e32 v182, 2, v166
	ds_bpermute_b32 v166, v182, v164
	s_addc_u32 s7, s61, s5
	s_and_b64 s[0:1], s[0:1], exec
	s_cselect_b32 s0, 0, 0x8000000
	s_cselect_b32 s9, s61, 0
	s_waitcnt lgkmcnt(0)
	v_add_f32_e32 v164, v164, v166
	v_xor_b32_e32 v166, 2, v233
	v_cmp_lt_i32_e32 vcc, v166, v165
	s_cselect_b32 s8, s60, s2
	s_add_u32 s2, s30, s0
	v_cndmask_b32_e32 v166, v233, v166, vcc
	v_lshlrev_b32_e32 v183, 2, v166
	ds_bpermute_b32 v166, v183, v164
	s_addc_u32 s10, s31, 0
	s_mov_b64 s[60:61], s[6:7]
	s_waitcnt lgkmcnt(0)
	v_add_f32_e32 v164, v164, v166
	v_xor_b32_e32 v166, 4, v233
	v_cmp_lt_i32_e32 vcc, v166, v165
	s_nop 1
	v_cndmask_b32_e32 v166, v233, v166, vcc
	v_lshlrev_b32_e32 v184, 2, v166
	ds_bpermute_b32 v166, v184, v164
	s_waitcnt lgkmcnt(0)
	v_add_f32_e32 v164, v164, v166
	v_xor_b32_e32 v166, 8, v233
	v_cmp_lt_i32_e32 vcc, v166, v165
	s_nop 1
	v_cndmask_b32_e32 v166, v233, v166, vcc
	v_lshlrev_b32_e32 v185, 2, v166
	ds_bpermute_b32 v166, v185, v164
	s_waitcnt lgkmcnt(0)
	v_add_f32_e32 v164, v164, v166
	v_xor_b32_e32 v166, 16, v233
	v_cmp_lt_i32_e32 vcc, v166, v165
	s_nop 1
	v_cndmask_b32_e32 v166, v233, v166, vcc
	v_lshlrev_b32_e32 v186, 2, v166
	ds_bpermute_b32 v166, v186, v164
	s_waitcnt lgkmcnt(0)
	v_add_f32_e32 v164, v164, v166
	v_xor_b32_e32 v166, 32, v233
	v_cmp_lt_i32_e32 vcc, v166, v165
	s_nop 1
	v_cndmask_b32_e32 v165, v233, v166, vcc
	v_lshlrev_b32_e32 v187, 2, v165
	ds_bpermute_b32 v165, v187, v164
	s_waitcnt lgkmcnt(0)
	v_add_f32_e32 v188, v164, v165
	v_fmamk_f32 v179, v188, 0xb9800000, v67
	v_fmamk_f32 v178, v188, 0xb9800000, v66
	v_fmamk_f32 v69, v188, 0xb9800000, v69
	v_fmac_f32_e32 v68, 0xb9800000, v188
	v_pk_mul_f32 v[66:67], v[68:69], v[68:69]
	v_pk_mul_f32 v[164:165], v[178:179], v[178:179]
	v_fmamk_f32 v175, v188, 0xb9800000, v71
	v_pk_mov_b32 v[166:167], v[164:165], v[66:67] op_sel:[1,0]
	v_mov_b32_e32 v165, v67
	v_pk_add_f32 v[66:67], v[166:167], v[164:165]
	v_fmamk_f32 v174, v188, 0xb9800000, v70
	v_fmamk_f32 v73, v188, 0xb9800000, v73
	v_fmac_f32_e32 v72, 0xb9800000, v188
	v_pk_add_f32 v[66:67], v[66:67], v[66:67] op_sel_hi:[0,1]
	v_pk_mul_f32 v[70:71], v[72:73], v[72:73]
	v_pk_mul_f32 v[164:165], v[174:175], v[174:175]
	v_fmamk_f32 v176, v188, 0xb9800000, v78
	v_pk_mov_b32 v[166:167], v[164:165], v[70:71] op_sel:[1,0]
	v_mov_b32_e32 v165, v71
	v_fmamk_f32 v177, v188, 0xb9800000, v79
	v_fmac_f32_e32 v80, 0xb9800000, v188
	v_mul_f32_e32 v66, v176, v176
	v_pk_add_f32 v[70:71], v[166:167], v[164:165]
	v_fmamk_f32 v81, v188, 0xb9800000, v81
	v_pk_fma_f32 v[78:79], v[176:177], v[176:177], v[66:67] op_sel_hi:[1,1,0]
	v_mul_f32_e32 v66, v80, v80
	v_pk_add_f32 v[70:71], v[70:71], v[70:71] op_sel_hi:[0,1]
	v_pk_fma_f32 v[164:165], v[80:81], v[80:81], v[66:67] op_sel_hi:[1,1,0]
	v_fmamk_f32 v171, v188, 0xb9800000, v85
	v_fmamk_f32 v170, v188, 0xb9800000, v84
	v_fmamk_f32 v83, v188, 0xb9800000, v83
	v_fmac_f32_e32 v82, 0xb9800000, v188
	v_mul_f32_e32 v78, v82, v82
	v_mul_f32_e32 v164, v83, v83
	v_mul_f32_e32 v66, v170, v170
	v_mul_f32_e32 v70, v171, v171
	v_pk_add_f32 v[78:79], v[78:79], v[164:165]
	v_pk_add_f32 v[66:67], v[66:67], v[70:71]
	v_fmamk_f32 v173, v188, 0xb9800000, v87
	v_pk_add_f32 v[66:67], v[78:79], v[66:67]
	v_fmamk_f32 v172, v188, 0xb9800000, v86
	v_fmamk_f32 v89, v188, 0xb9800000, v89
	v_fmac_f32_e32 v88, 0xb9800000, v188
	v_pk_add_f32 v[66:67], v[66:67], v[66:67] op_sel_hi:[0,1]
	v_pk_mul_f32 v[70:71], v[88:89], v[88:89]
	v_pk_mul_f32 v[78:79], v[172:173], v[172:173]
	v_fmamk_f32 v168, v188, 0xb9800000, v74
	v_pk_mov_b32 v[84:85], v[78:79], v[70:71] op_sel:[1,0]
	v_mov_b32_e32 v79, v71
	v_fmamk_f32 v169, v188, 0xb9800000, v75
	v_fmac_f32_e32 v76, 0xb9800000, v188
	v_mul_f32_e32 v66, v168, v168
	v_pk_add_f32 v[70:71], v[84:85], v[78:79]
	v_fmamk_f32 v77, v188, 0xb9800000, v77
	v_pk_fma_f32 v[74:75], v[168:169], v[168:169], v[66:67] op_sel_hi:[1,1,0]
	v_mul_f32_e32 v66, v76, v76
	v_pk_add_f32 v[70:71], v[70:71], v[70:71] op_sel_hi:[0,1]
	v_pk_fma_f32 v[78:79], v[76:77], v[76:77], v[66:67] op_sel_hi:[1,1,0]
	v_fmamk_f32 v165, v188, 0xb9800000, v93
	v_fmamk_f32 v164, v188, 0xb9800000, v92
	v_fmamk_f32 v91, v188, 0xb9800000, v91
	v_fmac_f32_e32 v90, 0xb9800000, v188
	v_mul_f32_e32 v74, v90, v90
	v_mul_f32_e32 v78, v91, v91
	v_mul_f32_e32 v70, v164, v164
	v_mul_f32_e32 v66, v165, v165
	v_pk_add_f32 v[74:75], v[74:75], v[78:79]
	v_pk_add_f32 v[66:67], v[70:71], v[66:67]
	v_fmamk_f32 v167, v188, 0xb9800000, v95
	v_pk_add_f32 v[66:67], v[74:75], v[66:67]
	v_fmamk_f32 v166, v188, 0xb9800000, v94
	v_fmamk_f32 v97, v188, 0xb9800000, v97
	v_fmac_f32_e32 v96, 0xb9800000, v188
	v_pk_add_f32 v[66:67], v[66:67], v[66:67] op_sel_hi:[0,1]
	v_pk_mul_f32 v[70:71], v[96:97], v[96:97]
	v_pk_mul_f32 v[74:75], v[166:167], v[166:167]
	v_fmamk_f32 v94, v188, 0xb9800000, v98
	v_pk_mov_b32 v[78:79], v[74:75], v[70:71] op_sel:[1,0]
	v_mov_b32_e32 v75, v71
	v_fmamk_f32 v95, v188, 0xb9800000, v99
	v_fmac_f32_e32 v100, 0xb9800000, v188
	v_mul_f32_e32 v66, v94, v94
	v_pk_add_f32 v[70:71], v[78:79], v[74:75]
	v_fmamk_f32 v101, v188, 0xb9800000, v101
	v_pk_fma_f32 v[74:75], v[94:95], v[94:95], v[66:67] op_sel_hi:[1,1,0]
	v_mul_f32_e32 v66, v100, v100
	v_pk_add_f32 v[70:71], v[70:71], v[70:71] op_sel_hi:[0,1]
	v_pk_fma_f32 v[78:79], v[100:101], v[100:101], v[66:67] op_sel_hi:[1,1,0]
	v_fmamk_f32 v85, v188, 0xb9800000, v105
	v_fmamk_f32 v84, v188, 0xb9800000, v104
	v_fmamk_f32 v103, v188, 0xb9800000, v103
	v_fmac_f32_e32 v102, 0xb9800000, v188
	v_mul_f32_e32 v74, v102, v102
	v_mul_f32_e32 v78, v103, v103
	v_mul_f32_e32 v70, v84, v84
	v_mul_f32_e32 v66, v85, v85
	v_pk_add_f32 v[74:75], v[74:75], v[78:79]
	v_pk_add_f32 v[66:67], v[70:71], v[66:67]
	v_fmamk_f32 v93, v188, 0xb9800000, v107
	v_pk_add_f32 v[66:67], v[74:75], v[66:67]
	v_fmamk_f32 v92, v188, 0xb9800000, v106
	v_fmamk_f32 v109, v188, 0xb9800000, v109
	v_fmac_f32_e32 v108, 0xb9800000, v188
	v_pk_add_f32 v[66:67], v[66:67], v[66:67] op_sel_hi:[0,1]
	v_pk_mul_f32 v[70:71], v[108:109], v[108:109]
	v_pk_mul_f32 v[74:75], v[92:93], v[92:93]
	v_fmamk_f32 v86, v188, 0xb9800000, v110
	v_pk_mov_b32 v[78:79], v[74:75], v[70:71] op_sel:[1,0]
	v_mov_b32_e32 v75, v71
	v_fmamk_f32 v87, v188, 0xb9800000, v111
	v_fmac_f32_e32 v112, 0xb9800000, v188
	v_mul_f32_e32 v66, v86, v86
	v_pk_add_f32 v[70:71], v[78:79], v[74:75]
	v_fmamk_f32 v113, v188, 0xb9800000, v113
	v_pk_fma_f32 v[74:75], v[86:87], v[86:87], v[66:67] op_sel_hi:[1,1,0]
	v_mul_f32_e32 v66, v112, v112
	v_pk_add_f32 v[70:71], v[70:71], v[70:71] op_sel_hi:[0,1]
	v_pk_fma_f32 v[98:99], v[112:113], v[112:113], v[66:67] op_sel_hi:[1,1,0]
	v_fmamk_f32 v79, v188, 0xb9800000, v117
	v_fmamk_f32 v78, v188, 0xb9800000, v116
	v_fmamk_f32 v115, v188, 0xb9800000, v115
	v_fmac_f32_e32 v114, 0xb9800000, v188
	v_mul_f32_e32 v74, v114, v114
	v_mul_f32_e32 v98, v115, v115
	v_mul_f32_e32 v70, v78, v78
	v_mul_f32_e32 v66, v79, v79
	v_pk_add_f32 v[74:75], v[74:75], v[98:99]
	v_pk_add_f32 v[66:67], v[70:71], v[66:67]
	v_fmamk_f32 v71, v188, 0xb9800000, v119
	v_pk_add_f32 v[66:67], v[74:75], v[66:67]
	v_fmamk_f32 v70, v188, 0xb9800000, v118
	v_fmamk_f32 v121, v188, 0xb9800000, v121
	v_fmac_f32_e32 v120, 0xb9800000, v188
	v_pk_add_f32 v[98:99], v[66:67], v[66:67] op_sel_hi:[0,1]
	v_pk_mul_f32 v[66:67], v[120:121], v[120:121]
	v_pk_mul_f32 v[74:75], v[70:71], v[70:71]
	v_fmac_f32_e32 v124, 0xb9800000, v188
	v_pk_mov_b32 v[104:105], v[74:75], v[66:67] op_sel:[1,0]
	v_mov_b32_e32 v75, v67
	v_pk_add_f32 v[66:67], v[104:105], v[74:75]
	v_fmamk_f32 v74, v188, 0xb9800000, v122
	v_pk_add_f32 v[104:105], v[66:67], v[66:67] op_sel_hi:[0,1]
	v_fmamk_f32 v75, v188, 0xb9800000, v123
	v_mul_f32_e32 v66, v74, v74
	v_fmamk_f32 v125, v188, 0xb9800000, v125
	v_pk_fma_f32 v[106:107], v[74:75], v[74:75], v[66:67] op_sel_hi:[1,1,0]
	v_mul_f32_e32 v66, v124, v124
	v_pk_fma_f32 v[110:111], v[124:125], v[124:125], v[66:67] op_sel_hi:[1,1,0]
	v_fmamk_f32 v67, v188, 0xb9800000, v129
	v_fmamk_f32 v66, v188, 0xb9800000, v128
	v_fmamk_f32 v127, v188, 0xb9800000, v127
	v_fmac_f32_e32 v126, 0xb9800000, v188
	v_mul_f32_e32 v106, v126, v126
	v_mul_f32_e32 v110, v127, v127
	v_mul_f32_e32 v104, v66, v66
	v_mul_f32_e32 v98, v67, v67
	v_pk_add_f32 v[106:107], v[106:107], v[110:111]
	v_pk_add_f32 v[98:99], v[104:105], v[98:99]
	s_nop 0
	v_pk_add_f32 v[98:99], v[106:107], v[98:99]
	s_nop 0
	v_add_f32_e32 v98, v98, v99
	ds_bpermute_b32 v99, v182, v98
	s_waitcnt lgkmcnt(0)
	v_add_f32_e32 v98, v98, v99
	ds_bpermute_b32 v99, v183, v98
	s_waitcnt lgkmcnt(0)
	v_add_f32_e32 v98, v98, v99
	ds_bpermute_b32 v99, v184, v98
	s_waitcnt lgkmcnt(0)
	v_add_f32_e32 v98, v98, v99
	ds_bpermute_b32 v99, v185, v98
	ds_read_b128 v[116:119], v230
	ds_read_b128 v[182:185], v230 offset:16384
	s_waitcnt lgkmcnt(2)
	v_add_f32_e32 v98, v98, v99
	ds_bpermute_b32 v99, v186, v98
	s_waitcnt lgkmcnt(0)
	v_add_f32_e32 v98, v98, v99
	ds_bpermute_b32 v99, v187, v98
	ds_read_b128 v[186:189], v230 offset:17408
	ds_read_b128 v[190:193], v230 offset:1024
	s_waitcnt lgkmcnt(2)
	v_add_f32_e32 v98, v98, v99
	v_fmamk_f32 v98, v98, 0x39800000, v231
	v_mul_f32_e32 v99, 0x4f800000, v98
	v_cmp_gt_f32_e32 vcc, s17, v98
	s_nop 1
	v_cndmask_b32_e32 v98, v98, v99, vcc
	v_sqrt_f32_e32 v99, v98
	s_nop 0
	v_add_u32_e32 v104, -1, v99
	v_fma_f32 v105, -v104, v99, v98
	v_cmp_ge_f32_e64 s[0:1], 0, v105
	v_add_u32_e32 v105, 1, v99
	s_nop 0
	v_cndmask_b32_e64 v104, v99, v104, s[0:1]
	v_fma_f32 v99, -v105, v99, v98
	v_cmp_lt_f32_e64 s[0:1], 0, v99
	s_nop 1
	v_cndmask_b32_e64 v99, v104, v105, s[0:1]
	v_mul_f32_e32 v104, 0x37800000, v99
	v_cndmask_b32_e32 v99, v99, v104, vcc
	v_cmp_class_f32_e32 vcc, v98, v232
	s_nop 1
	v_cndmask_b32_e32 v98, v99, v98, vcc
	v_div_scale_f32 v99, s[0:1], v98, v98, 1.0
	v_rcp_f32_e32 v104, v99
	s_lshl_b64 s[0:1], s[8:9], 14
	s_add_u32 s0, s2, s0
	s_addc_u32 s1, s10, s1
	v_fma_f32 v105, -v99, v104, 1.0
	v_fmac_f32_e32 v104, v105, v104
	v_div_scale_f32 v105, vcc, 1.0, v98, 1.0
	v_mul_f32_e32 v106, v105, v104
	v_fma_f32 v107, -v99, v106, v105
	v_fmac_f32_e32 v106, v107, v104
	v_fma_f32 v99, -v99, v106, v105
	v_div_fmas_f32 v99, v99, v104, v106
	v_div_fixup_f32 v98, v99, v98, 1.0
	v_pk_mul_f32 v[106:107], v[178:179], v[98:99] op_sel_hi:[1,0]
	v_pk_mul_f32 v[68:69], v[68:69], v[98:99] op_sel_hi:[1,0]
	v_pk_fma_f32 v[116:117], v[116:117], v[106:107], v[182:183]
	v_pk_fma_f32 v[118:119], v[118:119], v[68:69], v[184:185]
	v_pk_mul_f32 v[68:69], v[174:175], v[98:99] op_sel_hi:[1,0]
	v_pk_mul_f32 v[72:73], v[72:73], v[98:99] op_sel_hi:[1,0]
	global_store_dwordx4 v180, v[116:119], s[0:1] sc1
	v_lshl_add_u64 v[104:105], s[0:1], 0, v[180:181]
	v_pk_mul_f32 v[76:77], v[76:77], v[98:99] op_sel_hi:[1,0]
	s_waitcnt lgkmcnt(0)
	v_pk_fma_f32 v[118:119], v[192:193], v[72:73], v[188:189]
	v_pk_fma_f32 v[116:117], v[190:191], v[68:69], v[186:187]
	global_store_dwordx4 v180, v[116:119], s[0:1] offset:1024 sc1
	ds_read_b128 v[116:119], v230 offset:18432
	ds_read_b128 v[182:185], v230 offset:2048
	v_pk_mul_f32 v[68:69], v[176:177], v[98:99] op_sel_hi:[1,0]
	ds_read_b128 v[174:177], v230 offset:19456
	ds_read_b128 v[186:189], v230 offset:3072
	v_pk_mul_f32 v[72:73], v[80:81], v[98:99] op_sel_hi:[1,0]
	v_pk_mul_f32 v[106:107], v[90:91], v[98:99] op_sel_hi:[1,0]
	s_waitcnt lgkmcnt(2)
	v_pk_fma_f32 v[118:119], v[184:185], v[72:73], v[118:119]
	v_pk_fma_f32 v[116:117], v[182:183], v[68:69], v[116:117]
	v_pk_mul_f32 v[68:69], v[82:83], v[98:99] op_sel_hi:[1,0]
	v_pk_mul_f32 v[72:73], v[170:171], v[98:99] op_sel_hi:[1,0]
	s_waitcnt lgkmcnt(0)
	v_pk_fma_f32 v[80:81], v[186:187], v[68:69], v[174:175]
	v_pk_fma_f32 v[82:83], v[188:189], v[72:73], v[176:177]
	global_store_dwordx4 v180, v[116:119], s[0:1] offset:2048 sc1
	global_store_dwordx4 v180, v[80:83], s[0:1] offset:3072 sc1
	ds_read_b128 v[80:83], v230 offset:4096
	ds_read_b128 v[116:119], v230 offset:20480
	v_pk_mul_f32 v[68:69], v[88:89], v[98:99] op_sel_hi:[1,0]
	v_pk_mul_f32 v[72:73], v[172:173], v[98:99] op_sel_hi:[1,0]
	ds_read_b128 v[170:173], v230 offset:21504
	ds_read_b128 v[174:177], v230 offset:5120
	s_cmpk_lt_i32 s6, 0x2800
	s_waitcnt lgkmcnt(2)
	v_pk_fma_f32 v[82:83], v[82:83], v[68:69], v[118:119]
	v_add_co_u32_e32 v68, vcc, s15, v104
	v_pk_fma_f32 v[80:81], v[80:81], v[72:73], v[116:117]
	s_nop 0
	v_addc_co_u32_e32 v69, vcc, 0, v105, vcc
	v_add_co_u32_e32 v72, vcc, s14, v104
	s_nop 1
	v_addc_co_u32_e32 v73, vcc, 0, v105, vcc
	global_store_dwordx4 v[72:73], v[80:83], off offset:-4096 sc1
	s_nop 1
	v_pk_mul_f32 v[80:81], v[168:169], v[98:99] op_sel_hi:[1,0]
	s_waitcnt lgkmcnt(0)
	v_pk_fma_f32 v[82:83], v[176:177], v[76:77], v[172:173]
	v_pk_fma_f32 v[80:81], v[174:175], v[80:81], v[170:171]
	global_store_dwordx4 v[68:69], v[80:83], off offset:1024 sc1
	ds_read_b128 v[80:83], v230 offset:22528
	ds_read_b128 v[116:119], v230 offset:6144
	ds_read_b128 v[88:91], v230 offset:23552
	ds_read_b128 v[168:171], v230 offset:7168
	v_pk_mul_f32 v[76:77], v[164:165], v[98:99] op_sel_hi:[1,0]
	s_waitcnt lgkmcnt(2)
	v_pk_fma_f32 v[80:81], v[116:117], v[106:107], v[80:81]
	v_pk_fma_f32 v[82:83], v[118:119], v[76:77], v[82:83]
	global_store_dwordx4 v[68:69], v[80:83], off offset:2048 sc1
	v_pk_mul_f32 v[76:77], v[96:97], v[98:99] op_sel_hi:[1,0]
	s_nop 0
	v_pk_mul_f32 v[80:81], v[166:167], v[98:99] op_sel_hi:[1,0]
	s_waitcnt lgkmcnt(0)
	v_pk_fma_f32 v[82:83], v[170:171], v[76:77], v[90:91]
	v_pk_fma_f32 v[80:81], v[168:169], v[80:81], v[88:89]
	global_store_dwordx4 v[68:69], v[80:83], off offset:3072 sc1
	ds_read_b128 v[80:83], v230 offset:8192
	ds_read_b128 v[88:91], v230 offset:24576
	v_pk_mul_f32 v[76:77], v[94:95], v[98:99] op_sel_hi:[1,0]
	ds_read_b128 v[94:97], v230 offset:25600
	ds_read_b128 v[116:119], v230 offset:9216
	v_pk_mul_f32 v[68:69], v[100:101], v[98:99] op_sel_hi:[1,0]
	s_waitcnt lgkmcnt(2)
	v_pk_fma_f32 v[80:81], v[80:81], v[76:77], v[88:89]
	v_pk_fma_f32 v[82:83], v[82:83], v[68:69], v[90:91]
	v_pk_mul_f32 v[68:69], v[84:85], v[98:99] op_sel_hi:[1,0]
	v_pk_mul_f32 v[76:77], v[102:103], v[98:99] op_sel_hi:[1,0]
	global_store_dwordx4 v[72:73], v[80:83], off sc1
	s_waitcnt lgkmcnt(0)
	s_nop 0
	v_pk_fma_f32 v[80:81], v[116:117], v[76:77], v[94:95]
	v_pk_fma_f32 v[82:83], v[118:119], v[68:69], v[96:97]
	global_store_dwordx4 v[72:73], v[80:83], off offset:1024 sc1
	ds_read_b128 v[80:83], v230 offset:26624
	ds_read_b128 v[88:91], v230 offset:10240
	v_pk_mul_f32 v[76:77], v[92:93], v[98:99] op_sel_hi:[1,0]
	ds_read_b128 v[92:95], v230 offset:27648
	ds_read_b128 v[100:103], v230 offset:11264
	v_pk_mul_f32 v[68:69], v[108:109], v[98:99] op_sel_hi:[1,0]
	s_waitcnt lgkmcnt(2)
	v_pk_fma_f32 v[80:81], v[76:77], v[88:89], v[80:81]
	v_pk_fma_f32 v[82:83], v[68:69], v[90:91], v[82:83]
	v_pk_mul_f32 v[68:69], v[112:113], v[98:99] op_sel_hi:[1,0]
	v_pk_mul_f32 v[76:77], v[86:87], v[98:99] op_sel_hi:[1,0]
	global_store_dwordx4 v[72:73], v[80:83], off offset:2048 sc1
	s_waitcnt lgkmcnt(0)
	s_nop 0
	v_pk_fma_f32 v[80:81], v[76:77], v[100:101], v[92:93]
	v_pk_fma_f32 v[82:83], v[68:69], v[102:103], v[94:95]
	global_store_dwordx4 v[72:73], v[80:83], off offset:3072 sc1
	ds_read_b128 v[80:83], v230 offset:12288
	ds_read_b128 v[84:87], v230 offset:28672
	v_pk_mul_f32 v[68:69], v[78:79], v[98:99] op_sel_hi:[1,0]
	ds_read_b128 v[76:79], v230 offset:29696
	ds_read_b128 v[88:91], v230 offset:13312
	v_pk_mul_f32 v[72:73], v[114:115], v[98:99] op_sel_hi:[1,0]
	s_waitcnt lgkmcnt(2)
	v_pk_fma_f32 v[82:83], v[68:69], v[82:83], v[86:87]
	v_pk_fma_f32 v[80:81], v[72:73], v[80:81], v[84:85]
	v_add_co_u32_e32 v84, vcc, s16, v104
	v_pk_mul_f32 v[72:73], v[120:121], v[98:99] op_sel_hi:[1,0]
	v_pk_mul_f32 v[68:69], v[70:71], v[98:99] op_sel_hi:[1,0]
	v_addc_co_u32_e32 v85, vcc, 0, v105, vcc
	s_waitcnt lgkmcnt(0)
	v_pk_fma_f32 v[68:69], v[68:69], v[88:89], v[76:77]
	v_pk_fma_f32 v[70:71], v[72:73], v[90:91], v[78:79]
	global_store_dwordx4 v[84:85], v[80:83], off sc1
	global_store_dwordx4 v[84:85], v[68:71], off offset:1024 sc1
	ds_read_b128 v[68:71], v230 offset:30720
	ds_read_b128 v[76:79], v230 offset:14336
	v_pk_mul_f32 v[88:89], v[74:75], v[98:99] op_sel_hi:[1,0]
	ds_read_b128 v[72:75], v230 offset:31744
	ds_read_b128 v[80:83], v230 offset:15360
	v_pk_mul_f32 v[86:87], v[124:125], v[98:99] op_sel_hi:[1,0]
	s_waitcnt lgkmcnt(2)
	v_pk_fma_f32 v[68:69], v[88:89], v[76:77], v[68:69]
	v_pk_fma_f32 v[70:71], v[86:87], v[78:79], v[70:71]
	global_store_dwordx4 v[84:85], v[68:71], off offset:2048 sc1
	s_nop 1
	v_pk_mul_f32 v[68:69], v[66:67], v[98:99] op_sel_hi:[1,0]
	v_pk_mul_f32 v[66:67], v[126:127], v[98:99] op_sel_hi:[1,0]
	s_waitcnt lgkmcnt(0)
	v_pk_fma_f32 v[68:69], v[68:69], v[82:83], v[74:75]
	v_pk_fma_f32 v[66:67], v[66:67], v[80:81], v[72:73]
	global_store_dwordx4 v[84:85], v[66:69], off offset:3072 sc1
	s_cbranch_scc0 .LBB0_1121
